# speedup vs baseline: 1.0018x; 1.0018x over previous
.LBB0_1433:
	s_setprio 2
	v_readlane_b32 s20, v255, 15
	v_readlane_b32 s21, v255, 16
	s_load_dwordx2 s[20:21], s[20:21], 0x80
	s_ashr_i32 s22, s39, 2
	s_ashr_i32 s23, s22, 31
	s_lshl_b64 s[40:41], s[22:23], 19
	v_lshl_add_u64 v[136:137], v[206:207], 0, s[40:41]
	s_waitcnt lgkmcnt(0)
	s_add_u32 s2, s20, s31
	s_addc_u32 s19, s21, 0
	s_lshl_b32 s20, s39, 8
	s_and_b32 s20, s20, 0x300
	v_add_u32_e32 v14, s20, v230
	s_lshl_b32 s21, s22, 4
	v_lshl_or_b32 v138, v14, 4, v229
	s_and_b32 s21, s21, 0x3f0
	v_ashrrev_i32_e32 v139, 31, v138
	v_lshlrev_b64 v[14:15], 5, v[138:139]
	s_lshl_b32 s22, s21, 2
	v_lshl_add_u64 v[14:15], v[136:137], 0, v[14:15]
	s_add_u32 s22, s2, s22
	v_mov_b64_e32 v[180:181], v[14:15]
	s_addc_u32 s23, s19, 0
	global_load_dwordx4 v[14:17], v246, s[22:23]
	global_load_dwordx2 v[152:153], v[180:181], off
	global_load_dwordx2 v[154:155], v[180:181], off offset:32
	global_load_dwordx2 v[156:157], v[180:181], off offset:64
	global_load_dwordx2 v[158:159], v[180:181], off offset:96
	v_add_co_u32_e32 v180, vcc, 0x2000, v180
	s_nop 1
	v_addc_co_u32_e32 v181, vcc, 0, v181, vcc
	global_load_dwordx2 v[160:161], v[180:181], off
	global_load_dwordx2 v[162:163], v[180:181], off offset:32
	global_load_dwordx2 v[164:165], v[180:181], off offset:64
	global_load_dwordx2 v[166:167], v[180:181], off offset:96
	v_add_co_u32_e32 v180, vcc, 0x2000, v180
	s_nop 1
	v_addc_co_u32_e32 v181, vcc, 0, v181, vcc
	global_load_dwordx2 v[168:169], v[180:181], off
	global_load_dwordx2 v[170:171], v[180:181], off offset:32
	global_load_dwordx2 v[172:173], v[180:181], off offset:64
	global_load_dwordx2 v[174:175], v[180:181], off offset:96
	v_add_co_u32_e32 v180, vcc, 0x2000, v180
	s_nop 1
	v_addc_co_u32_e32 v181, vcc, 0, v181, vcc
	global_load_dwordx2 v[176:177], v[180:181], off
	global_load_dwordx2 v[178:179], v[180:181], off offset:32
	v_or_b32_e32 v142, 1, v138
	v_ashrrev_i32_e32 v143, 31, v142
	v_lshlrev_b64 v[146:147], 5, v[142:143]
	s_lshl_b32 s2, s39, 6
	s_and_b32 s19, s2, 0xffffc000
	v_add_u32_e32 v144, s19, v138
	s_lshl_b32 s68, s21, 1
	v_ashrrev_i32_e32 v145, 31, v144
	v_lshl_add_u64 v[134:135], v[208:209], 0, s[68:69]
	v_lshlrev_b64 v[144:145], 11, v[144:145]
	v_lshl_add_u64 v[144:145], v[134:135], 0, v[144:145]
	v_lshl_add_u64 v[146:147], v[136:137], 0, v[146:147]
	s_waitcnt vmcnt(13)
	v_mov_b64_e32 v[140:141], v[152:153]
	global_load_dwordx2 v[152:153], v[180:181], off offset:64
	v_lshlrev_b32_e32 v139, 16, v140
	v_and_b32_e32 v140, 0xffff0000, v140
	v_lshlrev_b32_e32 v143, 16, v141
	v_and_b32_e32 v141, 0xffff0000, v141
	v_fmac_f32_e32 v130, v14, v139
	v_fmac_f32_e32 v131, v15, v140
	v_fmac_f32_e32 v132, v16, v143
	v_fmac_f32_e32 v133, v17, v141
	v_mul_f32_e32 v139, 0x3d372713, v130
	v_mul_f32_e32 v141, 0x3d372713, v131
	v_mul_f32_e32 v148, 0x3d372713, v132
	v_mul_f32_e32 v150, 0x3d372713, v133
	v_mul_f32_e32 v139, v130, v139
	v_mul_f32_e32 v141, v131, v141
	v_mul_f32_e32 v140, 0.5, v130
	v_mul_f32_e32 v143, 0.5, v131
	v_mul_f32_e32 v148, v132, v148
	v_mul_f32_e32 v150, v133, v150
	v_fma_f32 v130, v130, v139, v130
	v_fma_f32 v131, v131, v141, v131
	v_mul_f32_e32 v149, 0.5, v132
	v_mul_f32_e32 v151, 0.5, v133
	v_fma_f32 v132, v132, v148, v132
	v_fma_f32 v133, v133, v150, v133
	v_mul_f32_e32 v130, 0x3f4c422a, v130
	v_mul_f32_e32 v131, 0x3f4c422a, v131
	v_mul_f32_e32 v132, 0x3f4c422a, v132
	v_mul_f32_e32 v133, 0x3f4c422a, v133
	v_add_f32_e32 v130, v130, v130
	v_add_f32_e32 v131, v131, v131
	v_add_f32_e32 v132, v132, v132
	v_add_f32_e32 v133, v133, v133
	v_mul_f32_e32 v130, 0x3fb8aa3b, v130
	v_mul_f32_e32 v131, 0x3fb8aa3b, v131
	v_mul_f32_e32 v132, 0x3fb8aa3b, v132
	v_mul_f32_e32 v133, 0x3fb8aa3b, v133
	v_exp_f32_e32 v130, v130
	v_exp_f32_e32 v131, v131
	v_exp_f32_e32 v132, v132
	v_exp_f32_e32 v133, v133
	v_add_f32_e32 v130, 1.0, v130
	v_add_f32_e32 v131, 1.0, v131
	v_add_f32_e32 v132, 1.0, v132
	v_add_f32_e32 v133, 1.0, v133
	v_rcp_f32_e32 v130, v130
	v_rcp_f32_e32 v131, v131
	v_rcp_f32_e32 v132, v132
	v_rcp_f32_e32 v133, v133
	v_fma_f32 v130, v130, -2.0, 1.0
	v_fma_f32 v131, v131, -2.0, 1.0
	v_fma_f32 v132, v132, -2.0, 1.0
	v_fma_f32 v133, v133, -2.0, 1.0
	v_add_f32_e32 v130, 1.0, v130
	v_add_f32_e32 v131, 1.0, v131
	v_add_f32_e32 v132, 1.0, v132
	v_add_f32_e32 v133, 1.0, v133
	v_mul_f32_e32 v130, v140, v130
	v_mul_f32_e32 v131, v143, v131
	v_mul_f32_e32 v132, v149, v132
	v_mul_f32_e32 v133, v151, v133
	v_cvt_pk_bf16_f32 v130, v130, v131
	v_cvt_pk_bf16_f32 v131, v132, v133
	global_store_dwordx2 v[144:145], v[130:131], off
	s_waitcnt vmcnt(14)
	v_mov_b64_e32 v[130:131], v[154:155]
	global_load_dwordx2 v[154:155], v[180:181], off offset:96
	v_add_co_u32_e32 v180, vcc, 0x2000, v180
	s_nop 1
	v_addc_co_u32_e32 v181, vcc, 0, v181, vcc
	v_or_b32_e32 v132, 2, v138
	v_ashrrev_i32_e32 v133, 31, v132
	v_add_u32_e32 v140, s19, v142
	v_lshlrev_b64 v[142:143], 5, v[132:133]
	v_ashrrev_i32_e32 v141, 31, v140
	v_lshlrev_b64 v[140:141], 11, v[140:141]
	v_lshl_add_u64 v[140:141], v[134:135], 0, v[140:141]
	v_lshl_add_u64 v[142:143], v[136:137], 0, v[142:143]
	v_lshlrev_b32_e32 v133, 16, v130
	v_and_b32_e32 v130, 0xffff0000, v130
	v_lshlrev_b32_e32 v139, 16, v131
	v_and_b32_e32 v131, 0xffff0000, v131
	v_fmac_f32_e32 v126, v14, v133
	v_fmac_f32_e32 v127, v15, v130
	v_fmac_f32_e32 v128, v16, v139
	v_fmac_f32_e32 v129, v17, v131
	v_mul_f32_e32 v130, 0x3d372713, v126
	v_mul_f32_e32 v133, 0x3d372713, v127
	v_mul_f32_e32 v144, 0x3d372713, v128
	v_mul_f32_e32 v146, 0x3d372713, v129
	v_mul_f32_e32 v130, v126, v130
	v_mul_f32_e32 v133, v127, v133
	v_mul_f32_e32 v131, 0.5, v126
	v_mul_f32_e32 v139, 0.5, v127
	v_mul_f32_e32 v144, v128, v144
	v_mul_f32_e32 v146, v129, v146
	v_fma_f32 v126, v126, v130, v126
	v_fma_f32 v127, v127, v133, v127
	v_mul_f32_e32 v145, 0.5, v128
	v_mul_f32_e32 v147, 0.5, v129
	v_fma_f32 v128, v128, v144, v128
	v_fma_f32 v129, v129, v146, v129
	v_mul_f32_e32 v126, 0x3f4c422a, v126
	v_mul_f32_e32 v127, 0x3f4c422a, v127
	v_mul_f32_e32 v128, 0x3f4c422a, v128
	v_mul_f32_e32 v129, 0x3f4c422a, v129
	v_add_f32_e32 v126, v126, v126
	v_add_f32_e32 v127, v127, v127
	v_add_f32_e32 v128, v128, v128
	v_add_f32_e32 v129, v129, v129
	v_mul_f32_e32 v126, 0x3fb8aa3b, v126
	v_mul_f32_e32 v127, 0x3fb8aa3b, v127
	v_mul_f32_e32 v128, 0x3fb8aa3b, v128
	v_mul_f32_e32 v129, 0x3fb8aa3b, v129
	v_exp_f32_e32 v126, v126
	v_exp_f32_e32 v127, v127
	v_exp_f32_e32 v128, v128
	v_exp_f32_e32 v129, v129
	v_add_f32_e32 v126, 1.0, v126
	v_add_f32_e32 v127, 1.0, v127
	v_add_f32_e32 v128, 1.0, v128
	v_add_f32_e32 v129, 1.0, v129
	v_rcp_f32_e32 v126, v126
	v_rcp_f32_e32 v127, v127
	v_rcp_f32_e32 v128, v128
	v_rcp_f32_e32 v129, v129
	v_fma_f32 v126, v126, -2.0, 1.0
	v_fma_f32 v127, v127, -2.0, 1.0
	v_fma_f32 v128, v128, -2.0, 1.0
	v_fma_f32 v129, v129, -2.0, 1.0
	v_add_f32_e32 v126, 1.0, v126
	v_add_f32_e32 v127, 1.0, v127
	v_add_f32_e32 v128, 1.0, v128
	v_add_f32_e32 v129, 1.0, v129
	v_mul_f32_e32 v126, v131, v126
	v_mul_f32_e32 v127, v139, v127
	v_mul_f32_e32 v128, v145, v128
	v_mul_f32_e32 v129, v147, v129
	v_cvt_pk_bf16_f32 v126, v126, v127
	v_cvt_pk_bf16_f32 v127, v128, v129
	global_store_dwordx2 v[140:141], v[126:127], off
	s_waitcnt vmcnt(15)
	v_mov_b64_e32 v[126:127], v[156:157]
	global_load_dwordx2 v[156:157], v[180:181], off
	v_or_b32_e32 v128, 3, v138
	v_ashrrev_i32_e32 v129, 31, v128
	v_add_u32_e32 v130, s19, v132
	v_lshlrev_b64 v[132:133], 5, v[128:129]
	v_ashrrev_i32_e32 v131, 31, v130
	v_lshlrev_b64 v[130:131], 11, v[130:131]
	v_lshl_add_u64 v[130:131], v[134:135], 0, v[130:131]
	v_lshl_add_u64 v[132:133], v[136:137], 0, v[132:133]
	v_lshlrev_b32_e32 v129, 16, v126
	v_and_b32_e32 v126, 0xffff0000, v126
	v_lshlrev_b32_e32 v138, 16, v127
	v_and_b32_e32 v127, 0xffff0000, v127
	v_fmac_f32_e32 v122, v14, v129
	v_fmac_f32_e32 v123, v15, v126
	v_fmac_f32_e32 v124, v16, v138
	v_fmac_f32_e32 v125, v17, v127
	v_mul_f32_e32 v126, 0x3d372713, v122
	v_mul_f32_e32 v129, 0x3d372713, v123
	v_mul_f32_e32 v139, 0x3d372713, v124
	v_mul_f32_e32 v141, 0x3d372713, v125
	v_mul_f32_e32 v126, v122, v126
	v_mul_f32_e32 v129, v123, v129
	v_mul_f32_e32 v127, 0.5, v122
	v_mul_f32_e32 v138, 0.5, v123
	v_mul_f32_e32 v139, v124, v139
	v_mul_f32_e32 v141, v125, v141
	v_fma_f32 v122, v122, v126, v122
	v_fma_f32 v123, v123, v129, v123
	v_mul_f32_e32 v140, 0.5, v124
	v_mul_f32_e32 v142, 0.5, v125
	v_fma_f32 v124, v124, v139, v124
	v_fma_f32 v125, v125, v141, v125
	v_mul_f32_e32 v122, 0x3f4c422a, v122
	v_mul_f32_e32 v123, 0x3f4c422a, v123
	v_mul_f32_e32 v124, 0x3f4c422a, v124
	v_mul_f32_e32 v125, 0x3f4c422a, v125
	v_add_f32_e32 v122, v122, v122
	v_add_f32_e32 v123, v123, v123
	v_add_f32_e32 v124, v124, v124
	v_add_f32_e32 v125, v125, v125
	v_mul_f32_e32 v122, 0x3fb8aa3b, v122
	v_mul_f32_e32 v123, 0x3fb8aa3b, v123
	v_mul_f32_e32 v124, 0x3fb8aa3b, v124
	v_mul_f32_e32 v125, 0x3fb8aa3b, v125
	v_exp_f32_e32 v122, v122
	v_exp_f32_e32 v123, v123
	v_exp_f32_e32 v124, v124
	v_exp_f32_e32 v125, v125
	v_add_f32_e32 v122, 1.0, v122
	v_add_f32_e32 v123, 1.0, v123
	v_add_f32_e32 v124, 1.0, v124
	v_add_f32_e32 v125, 1.0, v125
	v_rcp_f32_e32 v122, v122
	v_rcp_f32_e32 v123, v123
	v_rcp_f32_e32 v124, v124
	v_rcp_f32_e32 v125, v125
	v_fma_f32 v122, v122, -2.0, 1.0
	v_fma_f32 v123, v123, -2.0, 1.0
	v_fma_f32 v124, v124, -2.0, 1.0
	v_fma_f32 v125, v125, -2.0, 1.0
	v_add_f32_e32 v122, 1.0, v122
	v_add_f32_e32 v123, 1.0, v123
	v_add_f32_e32 v124, 1.0, v124
	v_add_f32_e32 v125, 1.0, v125
	v_mul_f32_e32 v122, v127, v122
	v_mul_f32_e32 v123, v138, v123
	v_mul_f32_e32 v124, v140, v124
	v_mul_f32_e32 v125, v142, v125
	v_cvt_pk_bf16_f32 v122, v122, v123
	v_cvt_pk_bf16_f32 v123, v124, v125
	global_store_dwordx2 v[130:131], v[122:123], off
	s_waitcnt vmcnt(16)
	v_mov_b64_e32 v[122:123], v[158:159]
	global_load_dwordx2 v[158:159], v[180:181], off offset:32
	v_add_u32_e32 v124, s19, v128
	v_ashrrev_i32_e32 v125, 31, v124
	v_lshlrev_b64 v[124:125], 11, v[124:125]
	v_lshlrev_b32_e32 v126, 16, v122
	v_and_b32_e32 v122, 0xffff0000, v122
	v_lshlrev_b32_e32 v127, 16, v123
	v_and_b32_e32 v123, 0xffff0000, v123
	v_fmac_f32_e32 v118, v14, v126
	v_fmac_f32_e32 v119, v15, v122
	v_fmac_f32_e32 v120, v16, v127
	v_fmac_f32_e32 v121, v17, v123
	v_mul_f32_e32 v122, 0x3d372713, v118
	v_mul_f32_e32 v126, 0x3d372713, v119
	v_mul_f32_e32 v128, 0x3d372713, v120
	v_mul_f32_e32 v130, 0x3d372713, v121
	v_mul_f32_e32 v122, v118, v122
	v_mul_f32_e32 v126, v119, v126
	v_mul_f32_e32 v128, v120, v128
	v_mul_f32_e32 v130, v121, v130
	v_mul_f32_e32 v123, 0.5, v118
	v_mul_f32_e32 v127, 0.5, v119
	v_mul_f32_e32 v129, 0.5, v120
	v_mul_f32_e32 v131, 0.5, v121
	v_fma_f32 v118, v118, v122, v118
	v_fma_f32 v119, v119, v126, v119
	v_fma_f32 v120, v120, v128, v120
	v_fma_f32 v121, v121, v130, v121
	v_mul_f32_e32 v118, 0x3f4c422a, v118
	v_mul_f32_e32 v119, 0x3f4c422a, v119
	v_mul_f32_e32 v120, 0x3f4c422a, v120
	v_mul_f32_e32 v121, 0x3f4c422a, v121
	v_add_f32_e32 v118, v118, v118
	v_add_f32_e32 v119, v119, v119
	v_add_f32_e32 v120, v120, v120
	v_add_f32_e32 v121, v121, v121
	v_mul_f32_e32 v118, 0x3fb8aa3b, v118
	v_mul_f32_e32 v119, 0x3fb8aa3b, v119
	v_mul_f32_e32 v120, 0x3fb8aa3b, v120
	v_mul_f32_e32 v121, 0x3fb8aa3b, v121
	v_exp_f32_e32 v118, v118
	v_exp_f32_e32 v119, v119
	v_exp_f32_e32 v120, v120
	v_exp_f32_e32 v121, v121
	v_add_f32_e32 v118, 1.0, v118
	v_add_f32_e32 v119, 1.0, v119
	v_add_f32_e32 v120, 1.0, v120
	v_add_f32_e32 v121, 1.0, v121
	v_rcp_f32_e32 v118, v118
	v_rcp_f32_e32 v119, v119
	v_rcp_f32_e32 v120, v120
	v_rcp_f32_e32 v121, v121
	v_fma_f32 v118, v118, -2.0, 1.0
	v_fma_f32 v119, v119, -2.0, 1.0
	v_fma_f32 v120, v120, -2.0, 1.0
	v_fma_f32 v121, v121, -2.0, 1.0
	v_add_f32_e32 v118, 1.0, v118
	v_add_f32_e32 v119, 1.0, v119
	v_add_f32_e32 v120, 1.0, v120
	v_add_f32_e32 v121, 1.0, v121
	v_mul_f32_e32 v118, v123, v118
	v_mul_f32_e32 v119, v127, v119
	v_mul_f32_e32 v120, v129, v120
	v_mul_f32_e32 v121, v131, v121
	v_cvt_pk_bf16_f32 v118, v118, v119
	v_cvt_pk_bf16_f32 v119, v120, v121
	v_lshl_add_u64 v[120:121], v[134:135], 0, v[124:125]
	global_store_dwordx2 v[120:121], v[118:119], off
	v_or_b32_e32 v118, 16, v230
	v_add_u32_e32 v118, s20, v118
	v_lshl_or_b32 v118, v118, 4, v229
	v_ashrrev_i32_e32 v119, 31, v118
	v_lshlrev_b64 v[120:121], 5, v[118:119]
	v_lshl_add_u64 v[120:121], v[136:137], 0, v[120:121]
	s_waitcnt vmcnt(17)
	v_mov_b64_e32 v[120:121], v[160:161]
	global_load_dwordx2 v[160:161], v[180:181], off offset:64
	v_lshlrev_b32_e32 v119, 16, v120
	v_fmac_f32_e32 v114, v14, v119
	v_mul_f32_e32 v119, 0x3d372713, v114
	v_mul_f32_e32 v119, v114, v119
	v_fma_f32 v119, v114, v119, v114
	v_mul_f32_e32 v119, 0x3f4c422a, v119
	v_add_f32_e32 v119, v119, v119
	v_mul_f32_e32 v119, 0x3fb8aa3b, v119
	v_exp_f32_e32 v119, v119
	v_mul_f32_e32 v114, 0.5, v114
	v_add_f32_e32 v119, 1.0, v119
	v_rcp_f32_e32 v119, v119
	s_nop 0
	v_fma_f32 v119, v119, -2.0, 1.0
	v_add_f32_e32 v119, 1.0, v119
	v_mul_f32_e32 v114, v114, v119
	v_and_b32_e32 v119, 0xffff0000, v120
	v_fmac_f32_e32 v115, v15, v119
	v_mul_f32_e32 v119, 0x3d372713, v115
	v_mul_f32_e32 v119, v115, v119
	v_fma_f32 v119, v115, v119, v115
	v_mul_f32_e32 v119, 0x3f4c422a, v119
	v_add_f32_e32 v119, v119, v119
	v_mul_f32_e32 v119, 0x3fb8aa3b, v119
	v_exp_f32_e32 v119, v119
	v_mul_f32_e32 v115, 0.5, v115
	v_add_f32_e32 v119, 1.0, v119
	v_rcp_f32_e32 v119, v119
	s_nop 0
	v_fma_f32 v119, v119, -2.0, 1.0
	v_add_f32_e32 v119, 1.0, v119
	v_mul_f32_e32 v115, v115, v119
	v_lshlrev_b32_e32 v119, 16, v121
	v_fmac_f32_e32 v116, v16, v119
	v_mul_f32_e32 v119, 0x3d372713, v116
	v_mul_f32_e32 v119, v116, v119
	v_fma_f32 v119, v116, v119, v116
	v_mul_f32_e32 v119, 0x3f4c422a, v119
	v_add_f32_e32 v119, v119, v119
	v_mul_f32_e32 v119, 0x3fb8aa3b, v119
	v_exp_f32_e32 v119, v119
	v_mul_f32_e32 v116, 0.5, v116
	v_cvt_pk_bf16_f32 v114, v114, v115
	v_add_f32_e32 v119, 1.0, v119
	v_rcp_f32_e32 v119, v119
	s_nop 0
	v_fma_f32 v119, v119, -2.0, 1.0
	v_add_f32_e32 v119, 1.0, v119
	v_mul_f32_e32 v116, v116, v119
	v_and_b32_e32 v119, 0xffff0000, v121
	v_fmac_f32_e32 v117, v17, v119
	v_mul_f32_e32 v119, 0x3d372713, v117
	v_mul_f32_e32 v119, v117, v119
	v_fma_f32 v119, v117, v119, v117
	v_mul_f32_e32 v119, 0x3f4c422a, v119
	v_add_f32_e32 v119, v119, v119
	v_mul_f32_e32 v119, 0x3fb8aa3b, v119
	v_exp_f32_e32 v119, v119
	v_mul_f32_e32 v117, 0.5, v117
	v_add_f32_e32 v119, 1.0, v119
	v_rcp_f32_e32 v119, v119
	s_nop 0
	v_fma_f32 v119, v119, -2.0, 1.0
	v_add_f32_e32 v119, 1.0, v119
	v_mul_f32_e32 v117, v117, v119
	v_cvt_pk_bf16_f32 v115, v116, v117
	v_add_u32_e32 v116, s19, v118
	v_ashrrev_i32_e32 v117, 31, v116
	v_lshlrev_b64 v[116:117], 11, v[116:117]
	v_lshl_add_u64 v[116:117], v[134:135], 0, v[116:117]
	global_store_dwordx2 v[116:117], v[114:115], off
	v_or_b32_e32 v114, 1, v118
	v_ashrrev_i32_e32 v115, 31, v114
	v_lshlrev_b64 v[116:117], 5, v[114:115]
	v_lshl_add_u64 v[116:117], v[136:137], 0, v[116:117]
	s_waitcnt vmcnt(18)
	v_mov_b64_e32 v[116:117], v[162:163]
	global_load_dwordx2 v[162:163], v[180:181], off offset:96
	v_add_co_u32_e32 v180, vcc, 0x2000, v180
	s_nop 1
	v_addc_co_u32_e32 v181, vcc, 0, v181, vcc
	v_lshlrev_b32_e32 v115, 16, v116
	v_fmac_f32_e32 v110, v14, v115
	v_mul_f32_e32 v115, 0x3d372713, v110
	v_mul_f32_e32 v115, v110, v115
	v_fma_f32 v115, v110, v115, v110
	v_mul_f32_e32 v115, 0x3f4c422a, v115
	v_add_f32_e32 v115, v115, v115
	v_mul_f32_e32 v115, 0x3fb8aa3b, v115
	v_exp_f32_e32 v115, v115
	v_mul_f32_e32 v110, 0.5, v110
	v_add_f32_e32 v115, 1.0, v115
	v_rcp_f32_e32 v115, v115
	s_nop 0
	v_fma_f32 v115, v115, -2.0, 1.0
	v_add_f32_e32 v115, 1.0, v115
	v_mul_f32_e32 v110, v110, v115
	v_and_b32_e32 v115, 0xffff0000, v116
	v_fmac_f32_e32 v111, v15, v115
	v_mul_f32_e32 v115, 0x3d372713, v111
	v_mul_f32_e32 v115, v111, v115
	v_fma_f32 v115, v111, v115, v111
	v_mul_f32_e32 v115, 0x3f4c422a, v115
	v_add_f32_e32 v115, v115, v115
	v_mul_f32_e32 v115, 0x3fb8aa3b, v115
	v_exp_f32_e32 v115, v115
	v_mul_f32_e32 v111, 0.5, v111
	v_add_f32_e32 v115, 1.0, v115
	v_rcp_f32_e32 v115, v115
	s_nop 0
	v_fma_f32 v115, v115, -2.0, 1.0
	v_add_f32_e32 v115, 1.0, v115
	v_mul_f32_e32 v111, v111, v115
	v_lshlrev_b32_e32 v115, 16, v117
	v_fmac_f32_e32 v112, v16, v115
	v_mul_f32_e32 v115, 0x3d372713, v112
	v_mul_f32_e32 v115, v112, v115
	v_fma_f32 v115, v112, v115, v112
	v_mul_f32_e32 v115, 0x3f4c422a, v115
	v_add_f32_e32 v115, v115, v115
	v_mul_f32_e32 v115, 0x3fb8aa3b, v115
	v_exp_f32_e32 v115, v115
	v_mul_f32_e32 v112, 0.5, v112
	v_cvt_pk_bf16_f32 v110, v110, v111
	v_add_f32_e32 v115, 1.0, v115
	v_rcp_f32_e32 v115, v115
	s_nop 0
	v_fma_f32 v115, v115, -2.0, 1.0
	v_add_f32_e32 v115, 1.0, v115
	v_mul_f32_e32 v112, v112, v115
	v_and_b32_e32 v115, 0xffff0000, v117
	v_fmac_f32_e32 v113, v17, v115
	v_mul_f32_e32 v115, 0x3d372713, v113
	v_mul_f32_e32 v115, v113, v115
	v_fma_f32 v115, v113, v115, v113
	v_mul_f32_e32 v115, 0x3f4c422a, v115
	v_add_f32_e32 v115, v115, v115
	v_mul_f32_e32 v115, 0x3fb8aa3b, v115
	v_exp_f32_e32 v115, v115
	v_mul_f32_e32 v113, 0.5, v113
	v_add_f32_e32 v115, 1.0, v115
	v_rcp_f32_e32 v115, v115
	s_nop 0
	v_fma_f32 v115, v115, -2.0, 1.0
	v_add_f32_e32 v115, 1.0, v115
	v_mul_f32_e32 v113, v113, v115
	v_cvt_pk_bf16_f32 v111, v112, v113
	v_add_u32_e32 v112, s19, v114
	v_ashrrev_i32_e32 v113, 31, v112
	v_lshlrev_b64 v[112:113], 11, v[112:113]
	v_lshl_add_u64 v[112:113], v[134:135], 0, v[112:113]
	global_store_dwordx2 v[112:113], v[110:111], off
	v_or_b32_e32 v110, 2, v118
	v_ashrrev_i32_e32 v111, 31, v110
	v_lshlrev_b64 v[112:113], 5, v[110:111]
	v_lshl_add_u64 v[112:113], v[136:137], 0, v[112:113]
	s_waitcnt vmcnt(19)
	v_mov_b64_e32 v[112:113], v[164:165]
	global_load_dwordx2 v[164:165], v[180:181], off
	v_lshlrev_b32_e32 v111, 16, v112
	v_fmac_f32_e32 v106, v14, v111
	v_mul_f32_e32 v111, 0x3d372713, v106
	v_mul_f32_e32 v111, v106, v111
	v_fma_f32 v111, v106, v111, v106
	v_mul_f32_e32 v111, 0x3f4c422a, v111
	v_add_f32_e32 v111, v111, v111
	v_mul_f32_e32 v111, 0x3fb8aa3b, v111
	v_exp_f32_e32 v111, v111
	v_mul_f32_e32 v106, 0.5, v106
	v_add_f32_e32 v111, 1.0, v111
	v_rcp_f32_e32 v111, v111
	s_nop 0
	v_fma_f32 v111, v111, -2.0, 1.0
	v_add_f32_e32 v111, 1.0, v111
	v_mul_f32_e32 v106, v106, v111
	v_and_b32_e32 v111, 0xffff0000, v112
	v_fmac_f32_e32 v107, v15, v111
	v_mul_f32_e32 v111, 0x3d372713, v107
	v_mul_f32_e32 v111, v107, v111
	v_fma_f32 v111, v107, v111, v107
	v_mul_f32_e32 v111, 0x3f4c422a, v111
	v_add_f32_e32 v111, v111, v111
	v_mul_f32_e32 v111, 0x3fb8aa3b, v111
	v_exp_f32_e32 v111, v111
	v_mul_f32_e32 v107, 0.5, v107
	v_add_f32_e32 v111, 1.0, v111
	v_rcp_f32_e32 v111, v111
	s_nop 0
	v_fma_f32 v111, v111, -2.0, 1.0
	v_add_f32_e32 v111, 1.0, v111
	v_mul_f32_e32 v107, v107, v111
	v_lshlrev_b32_e32 v111, 16, v113
	v_fmac_f32_e32 v108, v16, v111
	v_mul_f32_e32 v111, 0x3d372713, v108
	v_mul_f32_e32 v111, v108, v111
	v_fma_f32 v111, v108, v111, v108
	v_mul_f32_e32 v111, 0x3f4c422a, v111
	v_add_f32_e32 v111, v111, v111
	v_mul_f32_e32 v111, 0x3fb8aa3b, v111
	v_exp_f32_e32 v111, v111
	v_mul_f32_e32 v108, 0.5, v108
	v_cvt_pk_bf16_f32 v106, v106, v107
	v_add_f32_e32 v111, 1.0, v111
	v_rcp_f32_e32 v111, v111
	s_nop 0
	v_fma_f32 v111, v111, -2.0, 1.0
	v_add_f32_e32 v111, 1.0, v111
	v_mul_f32_e32 v108, v108, v111
	v_and_b32_e32 v111, 0xffff0000, v113
	v_fmac_f32_e32 v109, v17, v111
	v_mul_f32_e32 v111, 0x3d372713, v109
	v_mul_f32_e32 v111, v109, v111
	v_fma_f32 v111, v109, v111, v109
	v_mul_f32_e32 v111, 0x3f4c422a, v111
	v_add_f32_e32 v111, v111, v111
	v_mul_f32_e32 v111, 0x3fb8aa3b, v111
	v_exp_f32_e32 v111, v111
	v_mul_f32_e32 v109, 0.5, v109
	v_add_f32_e32 v111, 1.0, v111
	v_rcp_f32_e32 v111, v111
	s_nop 0
	v_fma_f32 v111, v111, -2.0, 1.0
	v_add_f32_e32 v111, 1.0, v111
	v_mul_f32_e32 v109, v109, v111
	v_cvt_pk_bf16_f32 v107, v108, v109
	v_add_u32_e32 v108, s19, v110
	v_ashrrev_i32_e32 v109, 31, v108
	v_lshlrev_b64 v[108:109], 11, v[108:109]
	v_lshl_add_u64 v[108:109], v[134:135], 0, v[108:109]
	global_store_dwordx2 v[108:109], v[106:107], off
	v_or_b32_e32 v106, 3, v118
	v_ashrrev_i32_e32 v107, 31, v106
	v_lshlrev_b64 v[108:109], 5, v[106:107]
	v_lshl_add_u64 v[108:109], v[136:137], 0, v[108:109]
	s_waitcnt vmcnt(20)
	v_mov_b64_e32 v[108:109], v[166:167]
	global_load_dwordx2 v[166:167], v[180:181], off offset:32
	v_lshlrev_b32_e32 v107, 16, v108
	v_fmac_f32_e32 v102, v14, v107
	v_mul_f32_e32 v107, 0x3d372713, v102
	v_mul_f32_e32 v107, v102, v107
	v_fma_f32 v107, v102, v107, v102
	v_mul_f32_e32 v107, 0x3f4c422a, v107
	v_add_f32_e32 v107, v107, v107
	v_mul_f32_e32 v107, 0x3fb8aa3b, v107
	v_exp_f32_e32 v107, v107
	v_mul_f32_e32 v102, 0.5, v102
	v_add_f32_e32 v107, 1.0, v107
	v_rcp_f32_e32 v107, v107
	s_nop 0
	v_fma_f32 v107, v107, -2.0, 1.0
	v_add_f32_e32 v107, 1.0, v107
	v_mul_f32_e32 v102, v102, v107
	v_and_b32_e32 v107, 0xffff0000, v108
	v_fmac_f32_e32 v103, v15, v107
	v_mul_f32_e32 v107, 0x3d372713, v103
	v_mul_f32_e32 v107, v103, v107
	v_fma_f32 v107, v103, v107, v103
	v_mul_f32_e32 v107, 0x3f4c422a, v107
	v_add_f32_e32 v107, v107, v107
	v_mul_f32_e32 v107, 0x3fb8aa3b, v107
	v_exp_f32_e32 v107, v107
	v_mul_f32_e32 v103, 0.5, v103
	v_add_f32_e32 v107, 1.0, v107
	v_rcp_f32_e32 v107, v107
	s_nop 0
	v_fma_f32 v107, v107, -2.0, 1.0
	v_add_f32_e32 v107, 1.0, v107
	v_mul_f32_e32 v103, v103, v107
	v_lshlrev_b32_e32 v107, 16, v109
	v_fmac_f32_e32 v104, v16, v107
	v_mul_f32_e32 v107, 0x3d372713, v104
	v_mul_f32_e32 v107, v104, v107
	v_fma_f32 v107, v104, v107, v104
	v_mul_f32_e32 v107, 0x3f4c422a, v107
	v_add_f32_e32 v107, v107, v107
	v_mul_f32_e32 v107, 0x3fb8aa3b, v107
	v_exp_f32_e32 v107, v107
	v_mul_f32_e32 v104, 0.5, v104
	v_cvt_pk_bf16_f32 v102, v102, v103
	v_add_f32_e32 v107, 1.0, v107
	v_rcp_f32_e32 v107, v107
	s_nop 0
	v_fma_f32 v107, v107, -2.0, 1.0
	v_add_f32_e32 v107, 1.0, v107
	v_mul_f32_e32 v104, v104, v107
	v_and_b32_e32 v107, 0xffff0000, v109
	v_fmac_f32_e32 v105, v17, v107
	v_mul_f32_e32 v107, 0x3d372713, v105
	v_mul_f32_e32 v107, v105, v107
	v_fma_f32 v107, v105, v107, v105
	v_mul_f32_e32 v107, 0x3f4c422a, v107
	v_add_f32_e32 v107, v107, v107
	v_mul_f32_e32 v107, 0x3fb8aa3b, v107
	v_exp_f32_e32 v107, v107
	v_mul_f32_e32 v105, 0.5, v105
	v_add_f32_e32 v107, 1.0, v107
	v_rcp_f32_e32 v107, v107
	s_nop 0
	v_fma_f32 v107, v107, -2.0, 1.0
	v_add_f32_e32 v107, 1.0, v107
	v_mul_f32_e32 v105, v105, v107
	v_cvt_pk_bf16_f32 v103, v104, v105
	v_add_u32_e32 v104, s19, v106
	v_ashrrev_i32_e32 v105, 31, v104
	v_lshlrev_b64 v[104:105], 11, v[104:105]
	v_lshl_add_u64 v[104:105], v[134:135], 0, v[104:105]
	global_store_dwordx2 v[104:105], v[102:103], off
	v_add_u32_e32 v102, s20, v231
	v_lshl_or_b32 v102, v102, 4, v229
	v_ashrrev_i32_e32 v103, 31, v102
	v_lshlrev_b64 v[104:105], 5, v[102:103]
	v_lshl_add_u64 v[104:105], v[136:137], 0, v[104:105]
	s_waitcnt vmcnt(21)
	v_mov_b64_e32 v[104:105], v[168:169]
	global_load_dwordx2 v[168:169], v[180:181], off offset:64
	v_lshlrev_b32_e32 v103, 16, v104
	v_fmac_f32_e32 v98, v14, v103
	v_mul_f32_e32 v103, 0x3d372713, v98
	v_mul_f32_e32 v103, v98, v103
	v_fma_f32 v103, v98, v103, v98
	v_mul_f32_e32 v103, 0x3f4c422a, v103
	v_add_f32_e32 v103, v103, v103
	v_mul_f32_e32 v103, 0x3fb8aa3b, v103
	v_exp_f32_e32 v103, v103
	v_mul_f32_e32 v98, 0.5, v98
	v_add_f32_e32 v103, 1.0, v103
	v_rcp_f32_e32 v103, v103
	s_nop 0
	v_fma_f32 v103, v103, -2.0, 1.0
	v_add_f32_e32 v103, 1.0, v103
	v_mul_f32_e32 v98, v98, v103
	v_and_b32_e32 v103, 0xffff0000, v104
	v_fmac_f32_e32 v99, v15, v103
	v_mul_f32_e32 v103, 0x3d372713, v99
	v_mul_f32_e32 v103, v99, v103
	v_fma_f32 v103, v99, v103, v99
	v_mul_f32_e32 v103, 0x3f4c422a, v103
	v_add_f32_e32 v103, v103, v103
	v_mul_f32_e32 v103, 0x3fb8aa3b, v103
	v_exp_f32_e32 v103, v103
	v_mul_f32_e32 v99, 0.5, v99
	v_add_f32_e32 v103, 1.0, v103
	v_rcp_f32_e32 v103, v103
	s_nop 0
	v_fma_f32 v103, v103, -2.0, 1.0
	v_add_f32_e32 v103, 1.0, v103
	v_mul_f32_e32 v99, v99, v103
	v_lshlrev_b32_e32 v103, 16, v105
	v_fmac_f32_e32 v100, v16, v103
	v_mul_f32_e32 v103, 0x3d372713, v100
	v_mul_f32_e32 v103, v100, v103
	v_fma_f32 v103, v100, v103, v100
	v_mul_f32_e32 v103, 0x3f4c422a, v103
	v_add_f32_e32 v103, v103, v103
	v_mul_f32_e32 v103, 0x3fb8aa3b, v103
	v_exp_f32_e32 v103, v103
	v_mul_f32_e32 v100, 0.5, v100
	v_cvt_pk_bf16_f32 v98, v98, v99
	v_add_f32_e32 v103, 1.0, v103
	v_rcp_f32_e32 v103, v103
	s_nop 0
	v_fma_f32 v103, v103, -2.0, 1.0
	v_add_f32_e32 v103, 1.0, v103
	v_mul_f32_e32 v100, v100, v103
	v_and_b32_e32 v103, 0xffff0000, v105
	v_fmac_f32_e32 v101, v17, v103
	v_mul_f32_e32 v103, 0x3d372713, v101
	v_mul_f32_e32 v103, v101, v103
	v_fma_f32 v103, v101, v103, v101
	v_mul_f32_e32 v103, 0x3f4c422a, v103
	v_add_f32_e32 v103, v103, v103
	v_mul_f32_e32 v103, 0x3fb8aa3b, v103
	v_exp_f32_e32 v103, v103
	v_mul_f32_e32 v101, 0.5, v101
	v_add_f32_e32 v103, 1.0, v103
	v_rcp_f32_e32 v103, v103
	s_nop 0
	v_fma_f32 v103, v103, -2.0, 1.0
	v_add_f32_e32 v103, 1.0, v103
	v_mul_f32_e32 v101, v101, v103
	v_cvt_pk_bf16_f32 v99, v100, v101
	v_add_u32_e32 v100, s19, v102
	v_ashrrev_i32_e32 v101, 31, v100
	v_lshlrev_b64 v[100:101], 11, v[100:101]
	v_lshl_add_u64 v[100:101], v[134:135], 0, v[100:101]
	global_store_dwordx2 v[100:101], v[98:99], off
	v_or_b32_e32 v98, 1, v102
	v_ashrrev_i32_e32 v99, 31, v98
	v_lshlrev_b64 v[100:101], 5, v[98:99]
	v_lshl_add_u64 v[100:101], v[136:137], 0, v[100:101]
	s_waitcnt vmcnt(22)
	v_mov_b64_e32 v[100:101], v[170:171]
	global_load_dwordx2 v[170:171], v[180:181], off offset:96
	v_add_co_u32_e32 v180, vcc, 0x2000, v180
	s_nop 1
	v_addc_co_u32_e32 v181, vcc, 0, v181, vcc
	v_lshlrev_b32_e32 v99, 16, v100
	v_fmac_f32_e32 v94, v14, v99
	v_mul_f32_e32 v99, 0x3d372713, v94
	v_mul_f32_e32 v99, v94, v99
	v_fma_f32 v99, v94, v99, v94
	v_mul_f32_e32 v99, 0x3f4c422a, v99
	v_add_f32_e32 v99, v99, v99
	v_mul_f32_e32 v99, 0x3fb8aa3b, v99
	v_exp_f32_e32 v99, v99
	v_mul_f32_e32 v94, 0.5, v94
	v_add_f32_e32 v99, 1.0, v99
	v_rcp_f32_e32 v99, v99
	s_nop 0
	v_fma_f32 v99, v99, -2.0, 1.0
	v_add_f32_e32 v99, 1.0, v99
	v_mul_f32_e32 v94, v94, v99
	v_and_b32_e32 v99, 0xffff0000, v100
	v_fmac_f32_e32 v95, v15, v99
	v_mul_f32_e32 v99, 0x3d372713, v95
	v_mul_f32_e32 v99, v95, v99
	v_fma_f32 v99, v95, v99, v95
	v_mul_f32_e32 v99, 0x3f4c422a, v99
	v_add_f32_e32 v99, v99, v99
	v_mul_f32_e32 v99, 0x3fb8aa3b, v99
	v_exp_f32_e32 v99, v99
	v_mul_f32_e32 v95, 0.5, v95
	v_add_f32_e32 v99, 1.0, v99
	v_rcp_f32_e32 v99, v99
	s_nop 0
	v_fma_f32 v99, v99, -2.0, 1.0
	v_add_f32_e32 v99, 1.0, v99
	v_mul_f32_e32 v95, v95, v99
	v_lshlrev_b32_e32 v99, 16, v101
	v_fmac_f32_e32 v96, v16, v99
	v_mul_f32_e32 v99, 0x3d372713, v96
	v_mul_f32_e32 v99, v96, v99
	v_fma_f32 v99, v96, v99, v96
	v_mul_f32_e32 v99, 0x3f4c422a, v99
	v_add_f32_e32 v99, v99, v99
	v_mul_f32_e32 v99, 0x3fb8aa3b, v99
	v_exp_f32_e32 v99, v99
	v_mul_f32_e32 v96, 0.5, v96
	v_cvt_pk_bf16_f32 v94, v94, v95
	v_add_f32_e32 v99, 1.0, v99
	v_rcp_f32_e32 v99, v99
	s_nop 0
	v_fma_f32 v99, v99, -2.0, 1.0
	v_add_f32_e32 v99, 1.0, v99
	v_mul_f32_e32 v96, v96, v99
	v_and_b32_e32 v99, 0xffff0000, v101
	v_fmac_f32_e32 v97, v17, v99
	v_mul_f32_e32 v99, 0x3d372713, v97
	v_mul_f32_e32 v99, v97, v99
	v_fma_f32 v99, v97, v99, v97
	v_mul_f32_e32 v99, 0x3f4c422a, v99
	v_add_f32_e32 v99, v99, v99
	v_mul_f32_e32 v99, 0x3fb8aa3b, v99
	v_exp_f32_e32 v99, v99
	v_mul_f32_e32 v97, 0.5, v97
	v_add_f32_e32 v99, 1.0, v99
	v_rcp_f32_e32 v99, v99
	s_nop 0
	v_fma_f32 v99, v99, -2.0, 1.0
	v_add_f32_e32 v99, 1.0, v99
	v_mul_f32_e32 v97, v97, v99
	v_cvt_pk_bf16_f32 v95, v96, v97
	v_add_u32_e32 v96, s19, v98
	v_ashrrev_i32_e32 v97, 31, v96
	v_lshlrev_b64 v[96:97], 11, v[96:97]
	v_lshl_add_u64 v[96:97], v[134:135], 0, v[96:97]
	global_store_dwordx2 v[96:97], v[94:95], off
	v_or_b32_e32 v94, 2, v102
	v_ashrrev_i32_e32 v95, 31, v94
	v_lshlrev_b64 v[96:97], 5, v[94:95]
	v_lshl_add_u64 v[96:97], v[136:137], 0, v[96:97]
	s_waitcnt vmcnt(23)
	v_mov_b64_e32 v[96:97], v[172:173]
	global_load_dwordx2 v[172:173], v[180:181], off
	v_lshlrev_b32_e32 v95, 16, v96
	v_fmac_f32_e32 v90, v14, v95
	v_mul_f32_e32 v95, 0x3d372713, v90
	v_mul_f32_e32 v95, v90, v95
	v_fma_f32 v95, v90, v95, v90
	v_mul_f32_e32 v95, 0x3f4c422a, v95
	v_add_f32_e32 v95, v95, v95
	v_mul_f32_e32 v95, 0x3fb8aa3b, v95
	v_exp_f32_e32 v95, v95
	v_mul_f32_e32 v90, 0.5, v90
	v_add_f32_e32 v95, 1.0, v95
	v_rcp_f32_e32 v95, v95
	s_nop 0
	v_fma_f32 v95, v95, -2.0, 1.0
	v_add_f32_e32 v95, 1.0, v95
	v_mul_f32_e32 v90, v90, v95
	v_and_b32_e32 v95, 0xffff0000, v96
	v_fmac_f32_e32 v91, v15, v95
	v_mul_f32_e32 v95, 0x3d372713, v91
	v_mul_f32_e32 v95, v91, v95
	v_fma_f32 v95, v91, v95, v91
	v_mul_f32_e32 v95, 0x3f4c422a, v95
	v_add_f32_e32 v95, v95, v95
	v_mul_f32_e32 v95, 0x3fb8aa3b, v95
	v_exp_f32_e32 v95, v95
	v_mul_f32_e32 v91, 0.5, v91
	v_add_f32_e32 v95, 1.0, v95
	v_rcp_f32_e32 v95, v95
	s_nop 0
	v_fma_f32 v95, v95, -2.0, 1.0
	v_add_f32_e32 v95, 1.0, v95
	v_mul_f32_e32 v91, v91, v95
	v_lshlrev_b32_e32 v95, 16, v97
	v_fmac_f32_e32 v92, v16, v95
	v_mul_f32_e32 v95, 0x3d372713, v92
	v_mul_f32_e32 v95, v92, v95
	v_fma_f32 v95, v92, v95, v92
	v_mul_f32_e32 v95, 0x3f4c422a, v95
	v_add_f32_e32 v95, v95, v95
	v_mul_f32_e32 v95, 0x3fb8aa3b, v95
	v_exp_f32_e32 v95, v95
	v_mul_f32_e32 v92, 0.5, v92
	v_cvt_pk_bf16_f32 v90, v90, v91
	v_add_f32_e32 v95, 1.0, v95
	v_rcp_f32_e32 v95, v95
	s_nop 0
	v_fma_f32 v95, v95, -2.0, 1.0
	v_add_f32_e32 v95, 1.0, v95
	v_mul_f32_e32 v92, v92, v95
	v_and_b32_e32 v95, 0xffff0000, v97
	v_fmac_f32_e32 v93, v17, v95
	v_mul_f32_e32 v95, 0x3d372713, v93
	v_mul_f32_e32 v95, v93, v95
	v_fma_f32 v95, v93, v95, v93
	v_mul_f32_e32 v95, 0x3f4c422a, v95
	v_add_f32_e32 v95, v95, v95
	v_mul_f32_e32 v95, 0x3fb8aa3b, v95
	v_exp_f32_e32 v95, v95
	v_mul_f32_e32 v93, 0.5, v93
	v_add_f32_e32 v95, 1.0, v95
	v_rcp_f32_e32 v95, v95
	s_nop 0
	v_fma_f32 v95, v95, -2.0, 1.0
	v_add_f32_e32 v95, 1.0, v95
	v_mul_f32_e32 v93, v93, v95
	v_cvt_pk_bf16_f32 v91, v92, v93
	v_add_u32_e32 v92, s19, v94
	v_ashrrev_i32_e32 v93, 31, v92
	v_lshlrev_b64 v[92:93], 11, v[92:93]
	v_lshl_add_u64 v[92:93], v[134:135], 0, v[92:93]
	global_store_dwordx2 v[92:93], v[90:91], off
	v_or_b32_e32 v90, 3, v102
	v_ashrrev_i32_e32 v91, 31, v90
	v_lshlrev_b64 v[92:93], 5, v[90:91]
	v_lshl_add_u64 v[92:93], v[136:137], 0, v[92:93]
	s_waitcnt vmcnt(24)
	v_mov_b64_e32 v[92:93], v[174:175]
	global_load_dwordx2 v[174:175], v[180:181], off offset:32
	v_lshlrev_b32_e32 v91, 16, v92
	v_fmac_f32_e32 v86, v14, v91
	v_mul_f32_e32 v91, 0x3d372713, v86
	v_mul_f32_e32 v91, v86, v91
	v_fma_f32 v91, v86, v91, v86
	v_mul_f32_e32 v91, 0x3f4c422a, v91
	v_add_f32_e32 v91, v91, v91
	v_mul_f32_e32 v91, 0x3fb8aa3b, v91
	v_exp_f32_e32 v91, v91
	v_mul_f32_e32 v86, 0.5, v86
	v_add_f32_e32 v91, 1.0, v91
	v_rcp_f32_e32 v91, v91
	s_nop 0
	v_fma_f32 v91, v91, -2.0, 1.0
	v_add_f32_e32 v91, 1.0, v91
	v_mul_f32_e32 v86, v86, v91
	v_and_b32_e32 v91, 0xffff0000, v92
	v_fmac_f32_e32 v87, v15, v91
	v_mul_f32_e32 v91, 0x3d372713, v87
	v_mul_f32_e32 v91, v87, v91
	v_fma_f32 v91, v87, v91, v87
	v_mul_f32_e32 v91, 0x3f4c422a, v91
	v_add_f32_e32 v91, v91, v91
	v_mul_f32_e32 v91, 0x3fb8aa3b, v91
	v_exp_f32_e32 v91, v91
	v_mul_f32_e32 v87, 0.5, v87
	v_add_f32_e32 v91, 1.0, v91
	v_rcp_f32_e32 v91, v91
	s_nop 0
	v_fma_f32 v91, v91, -2.0, 1.0
	v_add_f32_e32 v91, 1.0, v91
	v_mul_f32_e32 v87, v87, v91
	v_lshlrev_b32_e32 v91, 16, v93
	v_fmac_f32_e32 v88, v16, v91
	v_mul_f32_e32 v91, 0x3d372713, v88
	v_mul_f32_e32 v91, v88, v91
	v_fma_f32 v91, v88, v91, v88
	v_mul_f32_e32 v91, 0x3f4c422a, v91
	v_add_f32_e32 v91, v91, v91
	v_mul_f32_e32 v91, 0x3fb8aa3b, v91
	v_exp_f32_e32 v91, v91
	v_mul_f32_e32 v88, 0.5, v88
	v_cvt_pk_bf16_f32 v86, v86, v87
	v_add_f32_e32 v91, 1.0, v91
	v_rcp_f32_e32 v91, v91
	s_nop 0
	v_fma_f32 v91, v91, -2.0, 1.0
	v_add_f32_e32 v91, 1.0, v91
	v_mul_f32_e32 v88, v88, v91
	v_and_b32_e32 v91, 0xffff0000, v93
	v_fmac_f32_e32 v89, v17, v91
	v_mul_f32_e32 v91, 0x3d372713, v89
	v_mul_f32_e32 v91, v89, v91
	v_fma_f32 v91, v89, v91, v89
	v_mul_f32_e32 v91, 0x3f4c422a, v91
	v_add_f32_e32 v91, v91, v91
	v_mul_f32_e32 v91, 0x3fb8aa3b, v91
	v_exp_f32_e32 v91, v91
	v_mul_f32_e32 v89, 0.5, v89
	v_add_f32_e32 v91, 1.0, v91
	v_rcp_f32_e32 v91, v91
	s_nop 0
	v_fma_f32 v91, v91, -2.0, 1.0
	v_add_f32_e32 v91, 1.0, v91
	v_mul_f32_e32 v89, v89, v91
	v_cvt_pk_bf16_f32 v87, v88, v89
	v_add_u32_e32 v88, s19, v90
	v_ashrrev_i32_e32 v89, 31, v88
	v_lshlrev_b64 v[88:89], 11, v[88:89]
	v_lshl_add_u64 v[88:89], v[134:135], 0, v[88:89]
	global_store_dwordx2 v[88:89], v[86:87], off
	v_add_u32_e32 v86, s20, v232
	v_lshl_or_b32 v86, v86, 4, v229
	v_ashrrev_i32_e32 v87, 31, v86
	v_lshlrev_b64 v[88:89], 5, v[86:87]
	v_lshl_add_u64 v[88:89], v[136:137], 0, v[88:89]
	s_waitcnt vmcnt(25)
	v_mov_b64_e32 v[88:89], v[176:177]
	global_load_dwordx2 v[176:177], v[180:181], off offset:64
	v_lshlrev_b32_e32 v87, 16, v88
	v_fmac_f32_e32 v82, v14, v87
	v_mul_f32_e32 v87, 0x3d372713, v82
	v_mul_f32_e32 v87, v82, v87
	v_fma_f32 v87, v82, v87, v82
	v_mul_f32_e32 v87, 0x3f4c422a, v87
	v_add_f32_e32 v87, v87, v87
	v_mul_f32_e32 v87, 0x3fb8aa3b, v87
	v_exp_f32_e32 v87, v87
	v_mul_f32_e32 v82, 0.5, v82
	v_add_f32_e32 v87, 1.0, v87
	v_rcp_f32_e32 v87, v87
	s_nop 0
	v_fma_f32 v87, v87, -2.0, 1.0
	v_add_f32_e32 v87, 1.0, v87
	v_mul_f32_e32 v82, v82, v87
	v_and_b32_e32 v87, 0xffff0000, v88
	v_fmac_f32_e32 v83, v15, v87
	v_mul_f32_e32 v87, 0x3d372713, v83
	v_mul_f32_e32 v87, v83, v87
	v_fma_f32 v87, v83, v87, v83
	v_mul_f32_e32 v87, 0x3f4c422a, v87
	v_add_f32_e32 v87, v87, v87
	v_mul_f32_e32 v87, 0x3fb8aa3b, v87
	v_exp_f32_e32 v87, v87
	v_mul_f32_e32 v83, 0.5, v83
	v_add_f32_e32 v87, 1.0, v87
	v_rcp_f32_e32 v87, v87
	s_nop 0
	v_fma_f32 v87, v87, -2.0, 1.0
	v_add_f32_e32 v87, 1.0, v87
	v_mul_f32_e32 v83, v83, v87
	v_lshlrev_b32_e32 v87, 16, v89
	v_fmac_f32_e32 v84, v16, v87
	v_mul_f32_e32 v87, 0x3d372713, v84
	v_mul_f32_e32 v87, v84, v87
	v_fma_f32 v87, v84, v87, v84
	v_mul_f32_e32 v87, 0x3f4c422a, v87
	v_add_f32_e32 v87, v87, v87
	v_mul_f32_e32 v87, 0x3fb8aa3b, v87
	v_exp_f32_e32 v87, v87
	v_mul_f32_e32 v84, 0.5, v84
	v_cvt_pk_bf16_f32 v82, v82, v83
	v_add_f32_e32 v87, 1.0, v87
	v_rcp_f32_e32 v87, v87
	s_nop 0
	v_fma_f32 v87, v87, -2.0, 1.0
	v_add_f32_e32 v87, 1.0, v87
	v_mul_f32_e32 v84, v84, v87
	v_and_b32_e32 v87, 0xffff0000, v89
	v_fmac_f32_e32 v85, v17, v87
	v_mul_f32_e32 v87, 0x3d372713, v85
	v_mul_f32_e32 v87, v85, v87
	v_fma_f32 v87, v85, v87, v85
	v_mul_f32_e32 v87, 0x3f4c422a, v87
	v_add_f32_e32 v87, v87, v87
	v_mul_f32_e32 v87, 0x3fb8aa3b, v87
	v_exp_f32_e32 v87, v87
	v_mul_f32_e32 v85, 0.5, v85
	v_add_f32_e32 v87, 1.0, v87
	v_rcp_f32_e32 v87, v87
	s_nop 0
	v_fma_f32 v87, v87, -2.0, 1.0
	v_add_f32_e32 v87, 1.0, v87
	v_mul_f32_e32 v85, v85, v87
	v_cvt_pk_bf16_f32 v83, v84, v85
	v_add_u32_e32 v84, s19, v86
	v_ashrrev_i32_e32 v85, 31, v84
	v_lshlrev_b64 v[84:85], 11, v[84:85]
	v_lshl_add_u64 v[84:85], v[134:135], 0, v[84:85]
	global_store_dwordx2 v[84:85], v[82:83], off
	v_or_b32_e32 v82, 1, v86
	v_ashrrev_i32_e32 v83, 31, v82
	v_lshlrev_b64 v[84:85], 5, v[82:83]
	v_lshl_add_u64 v[84:85], v[136:137], 0, v[84:85]
	s_waitcnt vmcnt(26)
	v_mov_b64_e32 v[84:85], v[178:179]
	global_load_dwordx2 v[178:179], v[180:181], off offset:96
	v_add_co_u32_e32 v180, vcc, 0x2000, v180
	s_nop 1
	v_addc_co_u32_e32 v181, vcc, 0, v181, vcc
	v_lshlrev_b32_e32 v83, 16, v84
	v_fmac_f32_e32 v78, v14, v83
	v_mul_f32_e32 v83, 0x3d372713, v78
	v_mul_f32_e32 v83, v78, v83
	v_fma_f32 v83, v78, v83, v78
	v_mul_f32_e32 v83, 0x3f4c422a, v83
	v_add_f32_e32 v83, v83, v83
	v_mul_f32_e32 v83, 0x3fb8aa3b, v83
	v_exp_f32_e32 v83, v83
	v_mul_f32_e32 v78, 0.5, v78
	v_add_f32_e32 v83, 1.0, v83
	v_rcp_f32_e32 v83, v83
	s_nop 0
	v_fma_f32 v83, v83, -2.0, 1.0
	v_add_f32_e32 v83, 1.0, v83
	v_mul_f32_e32 v78, v78, v83
	v_and_b32_e32 v83, 0xffff0000, v84
	v_fmac_f32_e32 v79, v15, v83
	v_mul_f32_e32 v83, 0x3d372713, v79
	v_mul_f32_e32 v83, v79, v83
	v_fma_f32 v83, v79, v83, v79
	v_mul_f32_e32 v83, 0x3f4c422a, v83
	v_add_f32_e32 v83, v83, v83
	v_mul_f32_e32 v83, 0x3fb8aa3b, v83
	v_exp_f32_e32 v83, v83
	v_mul_f32_e32 v79, 0.5, v79
	v_add_f32_e32 v83, 1.0, v83
	v_rcp_f32_e32 v83, v83
	s_nop 0
	v_fma_f32 v83, v83, -2.0, 1.0
	v_add_f32_e32 v83, 1.0, v83
	v_mul_f32_e32 v79, v79, v83
	v_lshlrev_b32_e32 v83, 16, v85
	v_fmac_f32_e32 v80, v16, v83
	v_mul_f32_e32 v83, 0x3d372713, v80
	v_mul_f32_e32 v83, v80, v83
	v_fma_f32 v83, v80, v83, v80
	v_mul_f32_e32 v83, 0x3f4c422a, v83
	v_add_f32_e32 v83, v83, v83
	v_mul_f32_e32 v83, 0x3fb8aa3b, v83
	v_exp_f32_e32 v83, v83
	v_mul_f32_e32 v80, 0.5, v80
	v_cvt_pk_bf16_f32 v78, v78, v79
	v_add_f32_e32 v83, 1.0, v83
	v_rcp_f32_e32 v83, v83
	s_nop 0
	v_fma_f32 v83, v83, -2.0, 1.0
	v_add_f32_e32 v83, 1.0, v83
	v_mul_f32_e32 v80, v80, v83
	v_and_b32_e32 v83, 0xffff0000, v85
	v_fmac_f32_e32 v81, v17, v83
	v_mul_f32_e32 v83, 0x3d372713, v81
	v_mul_f32_e32 v83, v81, v83
	v_fma_f32 v83, v81, v83, v81
	v_mul_f32_e32 v83, 0x3f4c422a, v83
	v_add_f32_e32 v83, v83, v83
	v_mul_f32_e32 v83, 0x3fb8aa3b, v83
	v_exp_f32_e32 v83, v83
	v_mul_f32_e32 v81, 0.5, v81
	v_add_f32_e32 v83, 1.0, v83
	v_rcp_f32_e32 v83, v83
	s_nop 0
	v_fma_f32 v83, v83, -2.0, 1.0
	v_add_f32_e32 v83, 1.0, v83
	v_mul_f32_e32 v81, v81, v83
	v_cvt_pk_bf16_f32 v79, v80, v81
	v_add_u32_e32 v80, s19, v82
	v_ashrrev_i32_e32 v81, 31, v80
	v_lshlrev_b64 v[80:81], 11, v[80:81]
	v_lshl_add_u64 v[80:81], v[134:135], 0, v[80:81]
	global_store_dwordx2 v[80:81], v[78:79], off
	v_or_b32_e32 v78, 2, v86
	v_ashrrev_i32_e32 v79, 31, v78
	v_lshlrev_b64 v[80:81], 5, v[78:79]
	v_lshl_add_u64 v[80:81], v[136:137], 0, v[80:81]
	s_waitcnt vmcnt(27)
	v_mov_b64_e32 v[80:81], v[152:153]
	global_load_dwordx2 v[152:153], v[180:181], off
	v_lshlrev_b32_e32 v79, 16, v80
	v_fmac_f32_e32 v74, v14, v79
	v_mul_f32_e32 v79, 0x3d372713, v74
	v_mul_f32_e32 v79, v74, v79
	v_fma_f32 v79, v74, v79, v74
	v_mul_f32_e32 v79, 0x3f4c422a, v79
	v_add_f32_e32 v79, v79, v79
	v_mul_f32_e32 v79, 0x3fb8aa3b, v79
	v_exp_f32_e32 v79, v79
	v_mul_f32_e32 v74, 0.5, v74
	v_add_f32_e32 v79, 1.0, v79
	v_rcp_f32_e32 v79, v79
	s_nop 0
	v_fma_f32 v79, v79, -2.0, 1.0
	v_add_f32_e32 v79, 1.0, v79
	v_mul_f32_e32 v74, v74, v79
	v_and_b32_e32 v79, 0xffff0000, v80
	v_fmac_f32_e32 v75, v15, v79
	v_mul_f32_e32 v79, 0x3d372713, v75
	v_mul_f32_e32 v79, v75, v79
	v_fma_f32 v79, v75, v79, v75
	v_mul_f32_e32 v79, 0x3f4c422a, v79
	v_add_f32_e32 v79, v79, v79
	v_mul_f32_e32 v79, 0x3fb8aa3b, v79
	v_exp_f32_e32 v79, v79
	v_mul_f32_e32 v75, 0.5, v75
	v_add_f32_e32 v79, 1.0, v79
	v_rcp_f32_e32 v79, v79
	s_nop 0
	v_fma_f32 v79, v79, -2.0, 1.0
	v_add_f32_e32 v79, 1.0, v79
	v_mul_f32_e32 v75, v75, v79
	v_lshlrev_b32_e32 v79, 16, v81
	v_fmac_f32_e32 v76, v16, v79
	v_mul_f32_e32 v79, 0x3d372713, v76
	v_mul_f32_e32 v79, v76, v79
	v_fma_f32 v79, v76, v79, v76
	v_mul_f32_e32 v79, 0x3f4c422a, v79
	v_add_f32_e32 v79, v79, v79
	v_mul_f32_e32 v79, 0x3fb8aa3b, v79
	v_exp_f32_e32 v79, v79
	v_mul_f32_e32 v76, 0.5, v76
	v_cvt_pk_bf16_f32 v74, v74, v75
	v_add_f32_e32 v79, 1.0, v79
	v_rcp_f32_e32 v79, v79
	s_nop 0
	v_fma_f32 v79, v79, -2.0, 1.0
	v_add_f32_e32 v79, 1.0, v79
	v_mul_f32_e32 v76, v76, v79
	v_and_b32_e32 v79, 0xffff0000, v81
	v_fmac_f32_e32 v77, v17, v79
	v_mul_f32_e32 v79, 0x3d372713, v77
	v_mul_f32_e32 v79, v77, v79
	v_fma_f32 v79, v77, v79, v77
	v_mul_f32_e32 v79, 0x3f4c422a, v79
	v_add_f32_e32 v79, v79, v79
	v_mul_f32_e32 v79, 0x3fb8aa3b, v79
	v_exp_f32_e32 v79, v79
	v_mul_f32_e32 v77, 0.5, v77
	v_add_f32_e32 v79, 1.0, v79
	v_rcp_f32_e32 v79, v79
	s_nop 0
	v_fma_f32 v79, v79, -2.0, 1.0
	v_add_f32_e32 v79, 1.0, v79
	v_mul_f32_e32 v77, v77, v79
	v_cvt_pk_bf16_f32 v75, v76, v77
	v_add_u32_e32 v76, s19, v78
	v_ashrrev_i32_e32 v77, 31, v76
	v_lshlrev_b64 v[76:77], 11, v[76:77]
	v_lshl_add_u64 v[76:77], v[134:135], 0, v[76:77]
	global_store_dwordx2 v[76:77], v[74:75], off
	v_or_b32_e32 v74, 3, v86
	v_ashrrev_i32_e32 v75, 31, v74
	v_lshlrev_b64 v[76:77], 5, v[74:75]
	v_lshl_add_u64 v[76:77], v[136:137], 0, v[76:77]
	s_waitcnt vmcnt(27)
	v_mov_b64_e32 v[76:77], v[154:155]
	global_load_dwordx2 v[154:155], v[180:181], off offset:32
	v_lshlrev_b32_e32 v75, 16, v76
	v_fmac_f32_e32 v70, v14, v75
	v_mul_f32_e32 v75, 0x3d372713, v70
	v_mul_f32_e32 v75, v70, v75
	v_fma_f32 v75, v70, v75, v70
	v_mul_f32_e32 v75, 0x3f4c422a, v75
	v_add_f32_e32 v75, v75, v75
	v_mul_f32_e32 v75, 0x3fb8aa3b, v75
	v_exp_f32_e32 v75, v75
	v_mul_f32_e32 v70, 0.5, v70
	v_add_f32_e32 v75, 1.0, v75
	v_rcp_f32_e32 v75, v75
	s_nop 0
	v_fma_f32 v75, v75, -2.0, 1.0
	v_add_f32_e32 v75, 1.0, v75
	v_mul_f32_e32 v70, v70, v75
	v_and_b32_e32 v75, 0xffff0000, v76
	v_fmac_f32_e32 v71, v15, v75
	v_mul_f32_e32 v75, 0x3d372713, v71
	v_mul_f32_e32 v75, v71, v75
	v_fma_f32 v75, v71, v75, v71
	v_mul_f32_e32 v75, 0x3f4c422a, v75
	v_add_f32_e32 v75, v75, v75
	v_mul_f32_e32 v75, 0x3fb8aa3b, v75
	v_exp_f32_e32 v75, v75
	v_mul_f32_e32 v71, 0.5, v71
	v_add_f32_e32 v75, 1.0, v75
	v_rcp_f32_e32 v75, v75
	s_nop 0
	v_fma_f32 v75, v75, -2.0, 1.0
	v_add_f32_e32 v75, 1.0, v75
	v_mul_f32_e32 v71, v71, v75
	v_lshlrev_b32_e32 v75, 16, v77
	v_fmac_f32_e32 v72, v16, v75
	v_mul_f32_e32 v75, 0x3d372713, v72
	v_mul_f32_e32 v75, v72, v75
	v_fma_f32 v75, v72, v75, v72
	v_mul_f32_e32 v75, 0x3f4c422a, v75
	v_add_f32_e32 v75, v75, v75
	v_mul_f32_e32 v75, 0x3fb8aa3b, v75
	v_exp_f32_e32 v75, v75
	v_mul_f32_e32 v72, 0.5, v72
	v_cvt_pk_bf16_f32 v70, v70, v71
	v_add_f32_e32 v75, 1.0, v75
	v_rcp_f32_e32 v75, v75
	s_nop 0
	v_fma_f32 v75, v75, -2.0, 1.0
	v_add_f32_e32 v75, 1.0, v75
	v_mul_f32_e32 v72, v72, v75
	v_and_b32_e32 v75, 0xffff0000, v77
	v_fmac_f32_e32 v73, v17, v75
	v_mul_f32_e32 v75, 0x3d372713, v73
	v_mul_f32_e32 v75, v73, v75
	v_fma_f32 v75, v73, v75, v73
	v_mul_f32_e32 v75, 0x3f4c422a, v75
	v_add_f32_e32 v75, v75, v75
	v_mul_f32_e32 v75, 0x3fb8aa3b, v75
	v_exp_f32_e32 v75, v75
	v_mul_f32_e32 v73, 0.5, v73
	v_add_f32_e32 v75, 1.0, v75
	v_rcp_f32_e32 v75, v75
	s_nop 0
	v_fma_f32 v75, v75, -2.0, 1.0
	v_add_f32_e32 v75, 1.0, v75
	v_mul_f32_e32 v73, v73, v75
	v_cvt_pk_bf16_f32 v71, v72, v73
	v_add_u32_e32 v72, s19, v74
	v_ashrrev_i32_e32 v73, 31, v72
	v_lshlrev_b64 v[72:73], 11, v[72:73]
	v_lshl_add_u64 v[72:73], v[134:135], 0, v[72:73]
	global_store_dwordx2 v[72:73], v[70:71], off
	v_add_u32_e32 v70, s20, v233
	v_lshl_or_b32 v70, v70, 4, v229
	v_ashrrev_i32_e32 v71, 31, v70
	v_lshlrev_b64 v[72:73], 5, v[70:71]
	v_lshl_add_u64 v[72:73], v[136:137], 0, v[72:73]
	s_waitcnt vmcnt(27)
	v_mov_b64_e32 v[72:73], v[156:157]
	global_load_dwordx2 v[156:157], v[180:181], off offset:64
	v_lshlrev_b32_e32 v71, 16, v72
	v_fmac_f32_e32 v66, v14, v71
	v_mul_f32_e32 v71, 0x3d372713, v66
	v_mul_f32_e32 v71, v66, v71
	v_fma_f32 v71, v66, v71, v66
	v_mul_f32_e32 v71, 0x3f4c422a, v71
	v_add_f32_e32 v71, v71, v71
	v_mul_f32_e32 v71, 0x3fb8aa3b, v71
	v_exp_f32_e32 v71, v71
	v_mul_f32_e32 v66, 0.5, v66
	v_add_f32_e32 v71, 1.0, v71
	v_rcp_f32_e32 v71, v71
	s_nop 0
	v_fma_f32 v71, v71, -2.0, 1.0
	v_add_f32_e32 v71, 1.0, v71
	v_mul_f32_e32 v66, v66, v71
	v_and_b32_e32 v71, 0xffff0000, v72
	v_fmac_f32_e32 v67, v15, v71
	v_mul_f32_e32 v71, 0x3d372713, v67
	v_mul_f32_e32 v71, v67, v71
	v_fma_f32 v71, v67, v71, v67
	v_mul_f32_e32 v71, 0x3f4c422a, v71
	v_add_f32_e32 v71, v71, v71
	v_mul_f32_e32 v71, 0x3fb8aa3b, v71
	v_exp_f32_e32 v71, v71
	v_mul_f32_e32 v67, 0.5, v67
	v_add_f32_e32 v71, 1.0, v71
	v_rcp_f32_e32 v71, v71
	s_nop 0
	v_fma_f32 v71, v71, -2.0, 1.0
	v_add_f32_e32 v71, 1.0, v71
	v_mul_f32_e32 v67, v67, v71
	v_lshlrev_b32_e32 v71, 16, v73
	v_fmac_f32_e32 v68, v16, v71
	v_mul_f32_e32 v71, 0x3d372713, v68
	v_mul_f32_e32 v71, v68, v71
	v_fma_f32 v71, v68, v71, v68
	v_mul_f32_e32 v71, 0x3f4c422a, v71
	v_add_f32_e32 v71, v71, v71
	v_mul_f32_e32 v71, 0x3fb8aa3b, v71
	v_exp_f32_e32 v71, v71
	v_mul_f32_e32 v68, 0.5, v68
	v_cvt_pk_bf16_f32 v66, v66, v67
	v_add_f32_e32 v71, 1.0, v71
	v_rcp_f32_e32 v71, v71
	s_nop 0
	v_fma_f32 v71, v71, -2.0, 1.0
	v_add_f32_e32 v71, 1.0, v71
	v_mul_f32_e32 v68, v68, v71
	v_and_b32_e32 v71, 0xffff0000, v73
	v_fmac_f32_e32 v69, v17, v71
	v_mul_f32_e32 v71, 0x3d372713, v69
	v_mul_f32_e32 v71, v69, v71
	v_fma_f32 v71, v69, v71, v69
	v_mul_f32_e32 v71, 0x3f4c422a, v71
	v_add_f32_e32 v71, v71, v71
	v_mul_f32_e32 v71, 0x3fb8aa3b, v71
	v_exp_f32_e32 v71, v71
	v_mul_f32_e32 v69, 0.5, v69
	v_add_f32_e32 v71, 1.0, v71
	v_rcp_f32_e32 v71, v71
	s_nop 0
	v_fma_f32 v71, v71, -2.0, 1.0
	v_add_f32_e32 v71, 1.0, v71
	v_mul_f32_e32 v69, v69, v71
	v_cvt_pk_bf16_f32 v67, v68, v69
	v_add_u32_e32 v68, s19, v70
	v_ashrrev_i32_e32 v69, 31, v68
	v_lshlrev_b64 v[68:69], 11, v[68:69]
	v_lshl_add_u64 v[68:69], v[134:135], 0, v[68:69]
	global_store_dwordx2 v[68:69], v[66:67], off
	v_or_b32_e32 v66, 1, v70
	v_ashrrev_i32_e32 v67, 31, v66
	v_lshlrev_b64 v[68:69], 5, v[66:67]
	v_lshl_add_u64 v[68:69], v[136:137], 0, v[68:69]
	s_waitcnt vmcnt(27)
	v_mov_b64_e32 v[68:69], v[158:159]
	global_load_dwordx2 v[158:159], v[180:181], off offset:96
	v_lshlrev_b32_e32 v67, 16, v68
	v_fmac_f32_e32 v62, v14, v67
	v_mul_f32_e32 v67, 0x3d372713, v62
	v_mul_f32_e32 v67, v62, v67
	v_fma_f32 v67, v62, v67, v62
	v_mul_f32_e32 v67, 0x3f4c422a, v67
	v_add_f32_e32 v67, v67, v67
	v_mul_f32_e32 v67, 0x3fb8aa3b, v67
	v_exp_f32_e32 v67, v67
	v_mul_f32_e32 v62, 0.5, v62
	v_add_f32_e32 v67, 1.0, v67
	v_rcp_f32_e32 v67, v67
	s_nop 0
	v_fma_f32 v67, v67, -2.0, 1.0
	v_add_f32_e32 v67, 1.0, v67
	v_mul_f32_e32 v62, v62, v67
	v_and_b32_e32 v67, 0xffff0000, v68
	v_fmac_f32_e32 v63, v15, v67
	v_mul_f32_e32 v67, 0x3d372713, v63
	v_mul_f32_e32 v67, v63, v67
	v_fma_f32 v67, v63, v67, v63
	v_mul_f32_e32 v67, 0x3f4c422a, v67
	v_add_f32_e32 v67, v67, v67
	v_mul_f32_e32 v67, 0x3fb8aa3b, v67
	v_exp_f32_e32 v67, v67
	v_mul_f32_e32 v63, 0.5, v63
	v_add_f32_e32 v67, 1.0, v67
	v_rcp_f32_e32 v67, v67
	s_nop 0
	v_fma_f32 v67, v67, -2.0, 1.0
	v_add_f32_e32 v67, 1.0, v67
	v_mul_f32_e32 v63, v63, v67
	v_lshlrev_b32_e32 v67, 16, v69
	v_fmac_f32_e32 v64, v16, v67
	v_mul_f32_e32 v67, 0x3d372713, v64
	v_mul_f32_e32 v67, v64, v67
	v_fma_f32 v67, v64, v67, v64
	v_mul_f32_e32 v67, 0x3f4c422a, v67
	v_add_f32_e32 v67, v67, v67
	v_mul_f32_e32 v67, 0x3fb8aa3b, v67
	v_exp_f32_e32 v67, v67
	v_mul_f32_e32 v64, 0.5, v64
	v_cvt_pk_bf16_f32 v62, v62, v63
	v_add_f32_e32 v67, 1.0, v67
	v_rcp_f32_e32 v67, v67
	s_nop 0
	v_fma_f32 v67, v67, -2.0, 1.0
	v_add_f32_e32 v67, 1.0, v67
	v_mul_f32_e32 v64, v64, v67
	v_and_b32_e32 v67, 0xffff0000, v69
	v_fmac_f32_e32 v65, v17, v67
	v_mul_f32_e32 v67, 0x3d372713, v65
	v_mul_f32_e32 v67, v65, v67
	v_fma_f32 v67, v65, v67, v65
	v_mul_f32_e32 v67, 0x3f4c422a, v67
	v_add_f32_e32 v67, v67, v67
	v_mul_f32_e32 v67, 0x3fb8aa3b, v67
	v_exp_f32_e32 v67, v67
	v_mul_f32_e32 v65, 0.5, v65
	v_add_f32_e32 v67, 1.0, v67
	v_rcp_f32_e32 v67, v67
	s_nop 0
	v_fma_f32 v67, v67, -2.0, 1.0
	v_add_f32_e32 v67, 1.0, v67
	v_mul_f32_e32 v65, v65, v67
	v_cvt_pk_bf16_f32 v63, v64, v65
	v_add_u32_e32 v64, s19, v66
	v_ashrrev_i32_e32 v65, 31, v64
	v_lshlrev_b64 v[64:65], 11, v[64:65]
	v_lshl_add_u64 v[64:65], v[134:135], 0, v[64:65]
	global_store_dwordx2 v[64:65], v[62:63], off
	v_or_b32_e32 v62, 2, v70
	v_ashrrev_i32_e32 v63, 31, v62
	v_lshlrev_b64 v[64:65], 5, v[62:63]
	v_lshl_add_u64 v[64:65], v[136:137], 0, v[64:65]
	s_waitcnt vmcnt(27)
	v_mov_b64_e32 v[64:65], v[160:161]
	v_lshlrev_b32_e32 v63, 16, v64
	v_fmac_f32_e32 v58, v14, v63
	v_mul_f32_e32 v63, 0x3d372713, v58
	v_mul_f32_e32 v63, v58, v63
	v_fma_f32 v63, v58, v63, v58
	v_mul_f32_e32 v63, 0x3f4c422a, v63
	v_add_f32_e32 v63, v63, v63
	v_mul_f32_e32 v63, 0x3fb8aa3b, v63
	v_exp_f32_e32 v63, v63
	v_mul_f32_e32 v58, 0.5, v58
	v_add_f32_e32 v63, 1.0, v63
	v_rcp_f32_e32 v63, v63
	s_nop 0
	v_fma_f32 v63, v63, -2.0, 1.0
	v_add_f32_e32 v63, 1.0, v63
	v_mul_f32_e32 v58, v58, v63
	v_and_b32_e32 v63, 0xffff0000, v64
	v_fmac_f32_e32 v59, v15, v63
	v_mul_f32_e32 v63, 0x3d372713, v59
	v_mul_f32_e32 v63, v59, v63
	v_fma_f32 v63, v59, v63, v59
	v_mul_f32_e32 v63, 0x3f4c422a, v63
	v_add_f32_e32 v63, v63, v63
	v_mul_f32_e32 v63, 0x3fb8aa3b, v63
	v_exp_f32_e32 v63, v63
	v_mul_f32_e32 v59, 0.5, v59
	v_add_f32_e32 v63, 1.0, v63
	v_rcp_f32_e32 v63, v63
	s_nop 0
	v_fma_f32 v63, v63, -2.0, 1.0
	v_add_f32_e32 v63, 1.0, v63
	v_mul_f32_e32 v59, v59, v63
	v_lshlrev_b32_e32 v63, 16, v65
	v_fmac_f32_e32 v60, v16, v63
	v_mul_f32_e32 v63, 0x3d372713, v60
	v_mul_f32_e32 v63, v60, v63
	v_fma_f32 v63, v60, v63, v60
	v_mul_f32_e32 v63, 0x3f4c422a, v63
	v_add_f32_e32 v63, v63, v63
	v_mul_f32_e32 v63, 0x3fb8aa3b, v63
	v_exp_f32_e32 v63, v63
	v_mul_f32_e32 v60, 0.5, v60
	v_cvt_pk_bf16_f32 v58, v58, v59
	v_add_f32_e32 v63, 1.0, v63
	v_rcp_f32_e32 v63, v63
	s_nop 0
	v_fma_f32 v63, v63, -2.0, 1.0
	v_add_f32_e32 v63, 1.0, v63
	v_mul_f32_e32 v60, v60, v63
	v_and_b32_e32 v63, 0xffff0000, v65
	v_fmac_f32_e32 v61, v17, v63
	v_mul_f32_e32 v63, 0x3d372713, v61
	v_mul_f32_e32 v63, v61, v63
	v_fma_f32 v63, v61, v63, v61
	v_mul_f32_e32 v63, 0x3f4c422a, v63
	v_add_f32_e32 v63, v63, v63
	v_mul_f32_e32 v63, 0x3fb8aa3b, v63
	v_exp_f32_e32 v63, v63
	v_mul_f32_e32 v61, 0.5, v61
	v_add_f32_e32 v63, 1.0, v63
	v_rcp_f32_e32 v63, v63
	s_nop 0
	v_fma_f32 v63, v63, -2.0, 1.0
	v_add_f32_e32 v63, 1.0, v63
	v_mul_f32_e32 v61, v61, v63
	v_cvt_pk_bf16_f32 v59, v60, v61
	v_add_u32_e32 v60, s19, v62
	v_ashrrev_i32_e32 v61, 31, v60
	v_lshlrev_b64 v[60:61], 11, v[60:61]
	v_lshl_add_u64 v[60:61], v[134:135], 0, v[60:61]
	global_store_dwordx2 v[60:61], v[58:59], off
	v_or_b32_e32 v58, 3, v70
	v_ashrrev_i32_e32 v59, 31, v58
	v_lshlrev_b64 v[60:61], 5, v[58:59]
	v_lshl_add_u64 v[60:61], v[136:137], 0, v[60:61]
	s_waitcnt vmcnt(26)
	v_mov_b64_e32 v[60:61], v[162:163]
	v_lshlrev_b32_e32 v59, 16, v60
	v_fmac_f32_e32 v54, v14, v59
	v_mul_f32_e32 v59, 0x3d372713, v54
	v_mul_f32_e32 v59, v54, v59
	v_fma_f32 v59, v54, v59, v54
	v_mul_f32_e32 v59, 0x3f4c422a, v59
	v_add_f32_e32 v59, v59, v59
	v_mul_f32_e32 v59, 0x3fb8aa3b, v59
	v_exp_f32_e32 v59, v59
	v_mul_f32_e32 v54, 0.5, v54
	v_add_f32_e32 v59, 1.0, v59
	v_rcp_f32_e32 v59, v59
	s_nop 0
	v_fma_f32 v59, v59, -2.0, 1.0
	v_add_f32_e32 v59, 1.0, v59
	v_mul_f32_e32 v54, v54, v59
	v_and_b32_e32 v59, 0xffff0000, v60
	v_fmac_f32_e32 v55, v15, v59
	v_mul_f32_e32 v59, 0x3d372713, v55
	v_mul_f32_e32 v59, v55, v59
	v_fma_f32 v59, v55, v59, v55
	v_mul_f32_e32 v59, 0x3f4c422a, v59
	v_add_f32_e32 v59, v59, v59
	v_mul_f32_e32 v59, 0x3fb8aa3b, v59
	v_exp_f32_e32 v59, v59
	v_mul_f32_e32 v55, 0.5, v55
	v_add_f32_e32 v59, 1.0, v59
	v_rcp_f32_e32 v59, v59
	s_nop 0
	v_fma_f32 v59, v59, -2.0, 1.0
	v_add_f32_e32 v59, 1.0, v59
	v_mul_f32_e32 v55, v55, v59
	v_lshlrev_b32_e32 v59, 16, v61
	v_fmac_f32_e32 v56, v16, v59
	v_mul_f32_e32 v59, 0x3d372713, v56
	v_mul_f32_e32 v59, v56, v59
	v_fma_f32 v59, v56, v59, v56
	v_mul_f32_e32 v59, 0x3f4c422a, v59
	v_add_f32_e32 v59, v59, v59
	v_mul_f32_e32 v59, 0x3fb8aa3b, v59
	v_exp_f32_e32 v59, v59
	v_mul_f32_e32 v56, 0.5, v56
	v_cvt_pk_bf16_f32 v54, v54, v55
	v_add_f32_e32 v59, 1.0, v59
	v_rcp_f32_e32 v59, v59
	s_nop 0
	v_fma_f32 v59, v59, -2.0, 1.0
	v_add_f32_e32 v59, 1.0, v59
	v_mul_f32_e32 v56, v56, v59
	v_and_b32_e32 v59, 0xffff0000, v61
	v_fmac_f32_e32 v57, v17, v59
	v_mul_f32_e32 v59, 0x3d372713, v57
	v_mul_f32_e32 v59, v57, v59
	v_fma_f32 v59, v57, v59, v57
	v_mul_f32_e32 v59, 0x3f4c422a, v59
	v_add_f32_e32 v59, v59, v59
	v_mul_f32_e32 v59, 0x3fb8aa3b, v59
	v_exp_f32_e32 v59, v59
	v_mul_f32_e32 v57, 0.5, v57
	v_add_f32_e32 v59, 1.0, v59
	v_rcp_f32_e32 v59, v59
	s_nop 0
	v_fma_f32 v59, v59, -2.0, 1.0
	v_add_f32_e32 v59, 1.0, v59
	v_mul_f32_e32 v57, v57, v59
	v_cvt_pk_bf16_f32 v55, v56, v57
	v_add_u32_e32 v56, s19, v58
	v_ashrrev_i32_e32 v57, 31, v56
	v_lshlrev_b64 v[56:57], 11, v[56:57]
	v_lshl_add_u64 v[56:57], v[134:135], 0, v[56:57]
	global_store_dwordx2 v[56:57], v[54:55], off
	v_add_u32_e32 v54, s20, v234
	v_lshl_or_b32 v54, v54, 4, v229
	v_ashrrev_i32_e32 v55, 31, v54
	v_lshlrev_b64 v[56:57], 5, v[54:55]
	v_lshl_add_u64 v[56:57], v[136:137], 0, v[56:57]
	s_waitcnt vmcnt(25)
	v_mov_b64_e32 v[56:57], v[164:165]
	v_lshlrev_b32_e32 v55, 16, v56
	v_fmac_f32_e32 v50, v14, v55
	v_mul_f32_e32 v55, 0x3d372713, v50
	v_mul_f32_e32 v55, v50, v55
	v_fma_f32 v55, v50, v55, v50
	v_mul_f32_e32 v55, 0x3f4c422a, v55
	v_add_f32_e32 v55, v55, v55
	v_mul_f32_e32 v55, 0x3fb8aa3b, v55
	v_exp_f32_e32 v55, v55
	v_mul_f32_e32 v50, 0.5, v50
	v_add_f32_e32 v55, 1.0, v55
	v_rcp_f32_e32 v55, v55
	s_nop 0
	v_fma_f32 v55, v55, -2.0, 1.0
	v_add_f32_e32 v55, 1.0, v55
	v_mul_f32_e32 v50, v50, v55
	v_and_b32_e32 v55, 0xffff0000, v56
	v_fmac_f32_e32 v51, v15, v55
	v_mul_f32_e32 v55, 0x3d372713, v51
	v_mul_f32_e32 v55, v51, v55
	v_fma_f32 v55, v51, v55, v51
	v_mul_f32_e32 v55, 0x3f4c422a, v55
	v_add_f32_e32 v55, v55, v55
	v_mul_f32_e32 v55, 0x3fb8aa3b, v55
	v_exp_f32_e32 v55, v55
	v_mul_f32_e32 v51, 0.5, v51
	v_add_f32_e32 v55, 1.0, v55
	v_rcp_f32_e32 v55, v55
	s_nop 0
	v_fma_f32 v55, v55, -2.0, 1.0
	v_add_f32_e32 v55, 1.0, v55
	v_mul_f32_e32 v51, v51, v55
	v_lshlrev_b32_e32 v55, 16, v57
	v_fmac_f32_e32 v52, v16, v55
	v_mul_f32_e32 v55, 0x3d372713, v52
	v_mul_f32_e32 v55, v52, v55
	v_fma_f32 v55, v52, v55, v52
	v_mul_f32_e32 v55, 0x3f4c422a, v55
	v_add_f32_e32 v55, v55, v55
	v_mul_f32_e32 v55, 0x3fb8aa3b, v55
	v_exp_f32_e32 v55, v55
	v_mul_f32_e32 v52, 0.5, v52
	v_cvt_pk_bf16_f32 v50, v50, v51
	v_add_f32_e32 v55, 1.0, v55
	v_rcp_f32_e32 v55, v55
	s_nop 0
	v_fma_f32 v55, v55, -2.0, 1.0
	v_add_f32_e32 v55, 1.0, v55
	v_mul_f32_e32 v52, v52, v55
	v_and_b32_e32 v55, 0xffff0000, v57
	v_fmac_f32_e32 v53, v17, v55
	v_mul_f32_e32 v55, 0x3d372713, v53
	v_mul_f32_e32 v55, v53, v55
	v_fma_f32 v55, v53, v55, v53
	v_mul_f32_e32 v55, 0x3f4c422a, v55
	v_add_f32_e32 v55, v55, v55
	v_mul_f32_e32 v55, 0x3fb8aa3b, v55
	v_exp_f32_e32 v55, v55
	v_mul_f32_e32 v53, 0.5, v53
	v_add_f32_e32 v55, 1.0, v55
	v_rcp_f32_e32 v55, v55
	s_nop 0
	v_fma_f32 v55, v55, -2.0, 1.0
	v_add_f32_e32 v55, 1.0, v55
	v_mul_f32_e32 v53, v53, v55
	v_cvt_pk_bf16_f32 v51, v52, v53
	v_add_u32_e32 v52, s19, v54
	v_ashrrev_i32_e32 v53, 31, v52
	v_lshlrev_b64 v[52:53], 11, v[52:53]
	v_lshl_add_u64 v[52:53], v[134:135], 0, v[52:53]
	global_store_dwordx2 v[52:53], v[50:51], off
	v_or_b32_e32 v50, 1, v54
	v_ashrrev_i32_e32 v51, 31, v50
	v_lshlrev_b64 v[52:53], 5, v[50:51]
	v_lshl_add_u64 v[52:53], v[136:137], 0, v[52:53]
	s_waitcnt vmcnt(24)
	v_mov_b64_e32 v[52:53], v[166:167]
	v_lshlrev_b32_e32 v51, 16, v52
	v_fmac_f32_e32 v46, v14, v51
	v_mul_f32_e32 v51, 0x3d372713, v46
	v_mul_f32_e32 v51, v46, v51
	v_fma_f32 v51, v46, v51, v46
	v_mul_f32_e32 v51, 0x3f4c422a, v51
	v_add_f32_e32 v51, v51, v51
	v_mul_f32_e32 v51, 0x3fb8aa3b, v51
	v_exp_f32_e32 v51, v51
	v_mul_f32_e32 v46, 0.5, v46
	v_add_f32_e32 v51, 1.0, v51
	v_rcp_f32_e32 v51, v51
	s_nop 0
	v_fma_f32 v51, v51, -2.0, 1.0
	v_add_f32_e32 v51, 1.0, v51
	v_mul_f32_e32 v46, v46, v51
	v_and_b32_e32 v51, 0xffff0000, v52
	v_fmac_f32_e32 v47, v15, v51
	v_mul_f32_e32 v51, 0x3d372713, v47
	v_mul_f32_e32 v51, v47, v51
	v_fma_f32 v51, v47, v51, v47
	v_mul_f32_e32 v51, 0x3f4c422a, v51
	v_add_f32_e32 v51, v51, v51
	v_mul_f32_e32 v51, 0x3fb8aa3b, v51
	v_exp_f32_e32 v51, v51
	v_mul_f32_e32 v47, 0.5, v47
	v_add_f32_e32 v51, 1.0, v51
	v_rcp_f32_e32 v51, v51
	s_nop 0
	v_fma_f32 v51, v51, -2.0, 1.0
	v_add_f32_e32 v51, 1.0, v51
	v_mul_f32_e32 v47, v47, v51
	v_lshlrev_b32_e32 v51, 16, v53
	v_fmac_f32_e32 v48, v16, v51
	v_mul_f32_e32 v51, 0x3d372713, v48
	v_mul_f32_e32 v51, v48, v51
	v_fma_f32 v51, v48, v51, v48
	v_mul_f32_e32 v51, 0x3f4c422a, v51
	v_add_f32_e32 v51, v51, v51
	v_mul_f32_e32 v51, 0x3fb8aa3b, v51
	v_exp_f32_e32 v51, v51
	v_mul_f32_e32 v48, 0.5, v48
	v_cvt_pk_bf16_f32 v46, v46, v47
	v_add_f32_e32 v51, 1.0, v51
	v_rcp_f32_e32 v51, v51
	s_nop 0
	v_fma_f32 v51, v51, -2.0, 1.0
	v_add_f32_e32 v51, 1.0, v51
	v_mul_f32_e32 v48, v48, v51
	v_and_b32_e32 v51, 0xffff0000, v53
	v_fmac_f32_e32 v49, v17, v51
	v_mul_f32_e32 v51, 0x3d372713, v49
	v_mul_f32_e32 v51, v49, v51
	v_fma_f32 v51, v49, v51, v49
	v_mul_f32_e32 v51, 0x3f4c422a, v51
	v_add_f32_e32 v51, v51, v51
	v_mul_f32_e32 v51, 0x3fb8aa3b, v51
	v_exp_f32_e32 v51, v51
	v_mul_f32_e32 v49, 0.5, v49
	v_add_f32_e32 v51, 1.0, v51
	v_rcp_f32_e32 v51, v51
	s_nop 0
	v_fma_f32 v51, v51, -2.0, 1.0
	v_add_f32_e32 v51, 1.0, v51
	v_mul_f32_e32 v49, v49, v51
	v_cvt_pk_bf16_f32 v47, v48, v49
	v_add_u32_e32 v48, s19, v50
	v_ashrrev_i32_e32 v49, 31, v48
	v_lshlrev_b64 v[48:49], 11, v[48:49]
	v_lshl_add_u64 v[48:49], v[134:135], 0, v[48:49]
	global_store_dwordx2 v[48:49], v[46:47], off
	v_or_b32_e32 v46, 2, v54
	v_ashrrev_i32_e32 v47, 31, v46
	v_lshlrev_b64 v[48:49], 5, v[46:47]
	v_lshl_add_u64 v[48:49], v[136:137], 0, v[48:49]
	s_waitcnt vmcnt(23)
	v_mov_b64_e32 v[48:49], v[168:169]
	v_lshlrev_b32_e32 v47, 16, v48
	v_fmac_f32_e32 v42, v14, v47
	v_mul_f32_e32 v47, 0x3d372713, v42
	v_mul_f32_e32 v47, v42, v47
	v_fma_f32 v47, v42, v47, v42
	v_mul_f32_e32 v47, 0x3f4c422a, v47
	v_add_f32_e32 v47, v47, v47
	v_mul_f32_e32 v47, 0x3fb8aa3b, v47
	v_exp_f32_e32 v47, v47
	v_mul_f32_e32 v42, 0.5, v42
	v_add_f32_e32 v47, 1.0, v47
	v_rcp_f32_e32 v47, v47
	s_nop 0
	v_fma_f32 v47, v47, -2.0, 1.0
	v_add_f32_e32 v47, 1.0, v47
	v_mul_f32_e32 v42, v42, v47
	v_and_b32_e32 v47, 0xffff0000, v48
	v_fmac_f32_e32 v43, v15, v47
	v_mul_f32_e32 v47, 0x3d372713, v43
	v_mul_f32_e32 v47, v43, v47
	v_fma_f32 v47, v43, v47, v43
	v_mul_f32_e32 v47, 0x3f4c422a, v47
	v_add_f32_e32 v47, v47, v47
	v_mul_f32_e32 v47, 0x3fb8aa3b, v47
	v_exp_f32_e32 v47, v47
	v_mul_f32_e32 v43, 0.5, v43
	v_add_f32_e32 v47, 1.0, v47
	v_rcp_f32_e32 v47, v47
	s_nop 0
	v_fma_f32 v47, v47, -2.0, 1.0
	v_add_f32_e32 v47, 1.0, v47
	v_mul_f32_e32 v43, v43, v47
	v_lshlrev_b32_e32 v47, 16, v49
	v_fmac_f32_e32 v44, v16, v47
	v_mul_f32_e32 v47, 0x3d372713, v44
	v_mul_f32_e32 v47, v44, v47
	v_fma_f32 v47, v44, v47, v44
	v_mul_f32_e32 v47, 0x3f4c422a, v47
	v_add_f32_e32 v47, v47, v47
	v_mul_f32_e32 v47, 0x3fb8aa3b, v47
	v_exp_f32_e32 v47, v47
	v_mul_f32_e32 v44, 0.5, v44
	v_cvt_pk_bf16_f32 v42, v42, v43
	v_add_f32_e32 v47, 1.0, v47
	v_rcp_f32_e32 v47, v47
	s_nop 0
	v_fma_f32 v47, v47, -2.0, 1.0
	v_add_f32_e32 v47, 1.0, v47
	v_mul_f32_e32 v44, v44, v47
	v_and_b32_e32 v47, 0xffff0000, v49
	v_fmac_f32_e32 v45, v17, v47
	v_mul_f32_e32 v47, 0x3d372713, v45
	v_mul_f32_e32 v47, v45, v47
	v_fma_f32 v47, v45, v47, v45
	v_mul_f32_e32 v47, 0x3f4c422a, v47
	v_add_f32_e32 v47, v47, v47
	v_mul_f32_e32 v47, 0x3fb8aa3b, v47
	v_exp_f32_e32 v47, v47
	v_mul_f32_e32 v45, 0.5, v45
	v_add_f32_e32 v47, 1.0, v47
	v_rcp_f32_e32 v47, v47
	s_nop 0
	v_fma_f32 v47, v47, -2.0, 1.0
	v_add_f32_e32 v47, 1.0, v47
	v_mul_f32_e32 v45, v45, v47
	v_cvt_pk_bf16_f32 v43, v44, v45
	v_add_u32_e32 v44, s19, v46
	v_ashrrev_i32_e32 v45, 31, v44
	v_lshlrev_b64 v[44:45], 11, v[44:45]
	v_lshl_add_u64 v[44:45], v[134:135], 0, v[44:45]
	global_store_dwordx2 v[44:45], v[42:43], off
	v_or_b32_e32 v42, 3, v54
	v_ashrrev_i32_e32 v43, 31, v42
	v_lshlrev_b64 v[44:45], 5, v[42:43]
	v_lshl_add_u64 v[44:45], v[136:137], 0, v[44:45]
	s_waitcnt vmcnt(22)
	v_mov_b64_e32 v[44:45], v[170:171]
	v_lshlrev_b32_e32 v43, 16, v44
	v_fmac_f32_e32 v38, v14, v43
	v_mul_f32_e32 v43, 0x3d372713, v38
	v_mul_f32_e32 v43, v38, v43
	v_fma_f32 v43, v38, v43, v38
	v_mul_f32_e32 v43, 0x3f4c422a, v43
	v_add_f32_e32 v43, v43, v43
	v_mul_f32_e32 v43, 0x3fb8aa3b, v43
	v_exp_f32_e32 v43, v43
	v_mul_f32_e32 v38, 0.5, v38
	v_add_f32_e32 v43, 1.0, v43
	v_rcp_f32_e32 v43, v43
	s_nop 0
	v_fma_f32 v43, v43, -2.0, 1.0
	v_add_f32_e32 v43, 1.0, v43
	v_mul_f32_e32 v38, v38, v43
	v_and_b32_e32 v43, 0xffff0000, v44
	v_fmac_f32_e32 v39, v15, v43
	v_mul_f32_e32 v43, 0x3d372713, v39
	v_mul_f32_e32 v43, v39, v43
	v_fma_f32 v43, v39, v43, v39
	v_mul_f32_e32 v43, 0x3f4c422a, v43
	v_add_f32_e32 v43, v43, v43
	v_mul_f32_e32 v43, 0x3fb8aa3b, v43
	v_exp_f32_e32 v43, v43
	v_mul_f32_e32 v39, 0.5, v39
	v_add_f32_e32 v43, 1.0, v43
	v_rcp_f32_e32 v43, v43
	s_nop 0
	v_fma_f32 v43, v43, -2.0, 1.0
	v_add_f32_e32 v43, 1.0, v43
	v_mul_f32_e32 v39, v39, v43
	v_lshlrev_b32_e32 v43, 16, v45
	v_fmac_f32_e32 v40, v16, v43
	v_mul_f32_e32 v43, 0x3d372713, v40
	v_mul_f32_e32 v43, v40, v43
	v_fma_f32 v43, v40, v43, v40
	v_mul_f32_e32 v43, 0x3f4c422a, v43
	v_add_f32_e32 v43, v43, v43
	v_mul_f32_e32 v43, 0x3fb8aa3b, v43
	v_exp_f32_e32 v43, v43
	v_mul_f32_e32 v40, 0.5, v40
	v_cvt_pk_bf16_f32 v38, v38, v39
	v_add_f32_e32 v43, 1.0, v43
	v_rcp_f32_e32 v43, v43
	s_nop 0
	v_fma_f32 v43, v43, -2.0, 1.0
	v_add_f32_e32 v43, 1.0, v43
	v_mul_f32_e32 v40, v40, v43
	v_and_b32_e32 v43, 0xffff0000, v45
	v_fmac_f32_e32 v41, v17, v43
	v_mul_f32_e32 v43, 0x3d372713, v41
	v_mul_f32_e32 v43, v41, v43
	v_fma_f32 v43, v41, v43, v41
	v_mul_f32_e32 v43, 0x3f4c422a, v43
	v_add_f32_e32 v43, v43, v43
	v_mul_f32_e32 v43, 0x3fb8aa3b, v43
	v_exp_f32_e32 v43, v43
	v_mul_f32_e32 v41, 0.5, v41
	v_add_f32_e32 v43, 1.0, v43
	v_rcp_f32_e32 v43, v43
	s_nop 0
	v_fma_f32 v43, v43, -2.0, 1.0
	v_add_f32_e32 v43, 1.0, v43
	v_mul_f32_e32 v41, v41, v43
	v_cvt_pk_bf16_f32 v39, v40, v41
	v_add_u32_e32 v40, s19, v42
	v_ashrrev_i32_e32 v41, 31, v40
	v_lshlrev_b64 v[40:41], 11, v[40:41]
	v_lshl_add_u64 v[40:41], v[134:135], 0, v[40:41]
	global_store_dwordx2 v[40:41], v[38:39], off
	v_add_u32_e32 v38, s20, v235
	v_lshl_or_b32 v38, v38, 4, v229
	v_ashrrev_i32_e32 v39, 31, v38
	v_lshlrev_b64 v[40:41], 5, v[38:39]
	v_lshl_add_u64 v[40:41], v[136:137], 0, v[40:41]
	s_waitcnt vmcnt(21)
	v_mov_b64_e32 v[40:41], v[172:173]
	v_lshlrev_b32_e32 v39, 16, v40
	v_fmac_f32_e32 v34, v14, v39
	v_mul_f32_e32 v39, 0x3d372713, v34
	v_mul_f32_e32 v39, v34, v39
	v_fma_f32 v39, v34, v39, v34
	v_mul_f32_e32 v39, 0x3f4c422a, v39
	v_add_f32_e32 v39, v39, v39
	v_mul_f32_e32 v39, 0x3fb8aa3b, v39
	v_exp_f32_e32 v39, v39
	v_mul_f32_e32 v34, 0.5, v34
	v_add_f32_e32 v39, 1.0, v39
	v_rcp_f32_e32 v39, v39
	s_nop 0
	v_fma_f32 v39, v39, -2.0, 1.0
	v_add_f32_e32 v39, 1.0, v39
	v_mul_f32_e32 v34, v34, v39
	v_and_b32_e32 v39, 0xffff0000, v40
	v_fmac_f32_e32 v35, v15, v39
	v_mul_f32_e32 v39, 0x3d372713, v35
	v_mul_f32_e32 v39, v35, v39
	v_fma_f32 v39, v35, v39, v35
	v_mul_f32_e32 v39, 0x3f4c422a, v39
	v_add_f32_e32 v39, v39, v39
	v_mul_f32_e32 v39, 0x3fb8aa3b, v39
	v_exp_f32_e32 v39, v39
	v_mul_f32_e32 v35, 0.5, v35
	v_add_f32_e32 v39, 1.0, v39
	v_rcp_f32_e32 v39, v39
	s_nop 0
	v_fma_f32 v39, v39, -2.0, 1.0
	v_add_f32_e32 v39, 1.0, v39
	v_mul_f32_e32 v35, v35, v39
	v_lshlrev_b32_e32 v39, 16, v41
	v_fmac_f32_e32 v36, v16, v39
	v_mul_f32_e32 v39, 0x3d372713, v36
	v_mul_f32_e32 v39, v36, v39
	v_fma_f32 v39, v36, v39, v36
	v_mul_f32_e32 v39, 0x3f4c422a, v39
	v_add_f32_e32 v39, v39, v39
	v_mul_f32_e32 v39, 0x3fb8aa3b, v39
	v_exp_f32_e32 v39, v39
	v_mul_f32_e32 v36, 0.5, v36
	v_cvt_pk_bf16_f32 v34, v34, v35
	v_add_f32_e32 v39, 1.0, v39
	v_rcp_f32_e32 v39, v39
	s_nop 0
	v_fma_f32 v39, v39, -2.0, 1.0
	v_add_f32_e32 v39, 1.0, v39
	v_mul_f32_e32 v36, v36, v39
	v_and_b32_e32 v39, 0xffff0000, v41
	v_fmac_f32_e32 v37, v17, v39
	v_mul_f32_e32 v39, 0x3d372713, v37
	v_mul_f32_e32 v39, v37, v39
	v_fma_f32 v39, v37, v39, v37
	v_mul_f32_e32 v39, 0x3f4c422a, v39
	v_add_f32_e32 v39, v39, v39
	v_mul_f32_e32 v39, 0x3fb8aa3b, v39
	v_exp_f32_e32 v39, v39
	v_mul_f32_e32 v37, 0.5, v37
	v_add_f32_e32 v39, 1.0, v39
	v_rcp_f32_e32 v39, v39
	s_nop 0
	v_fma_f32 v39, v39, -2.0, 1.0
	v_add_f32_e32 v39, 1.0, v39
	v_mul_f32_e32 v37, v37, v39
	v_cvt_pk_bf16_f32 v35, v36, v37
	v_add_u32_e32 v36, s19, v38
	v_ashrrev_i32_e32 v37, 31, v36
	v_lshlrev_b64 v[36:37], 11, v[36:37]
	v_lshl_add_u64 v[36:37], v[134:135], 0, v[36:37]
	global_store_dwordx2 v[36:37], v[34:35], off
	v_or_b32_e32 v34, 1, v38
	v_ashrrev_i32_e32 v35, 31, v34
	v_lshlrev_b64 v[36:37], 5, v[34:35]
	v_lshl_add_u64 v[36:37], v[136:137], 0, v[36:37]
	s_waitcnt vmcnt(20)
	v_mov_b64_e32 v[36:37], v[174:175]
	v_lshlrev_b32_e32 v35, 16, v36
	v_fmac_f32_e32 v30, v14, v35
	v_mul_f32_e32 v35, 0x3d372713, v30
	v_mul_f32_e32 v35, v30, v35
	v_fma_f32 v35, v30, v35, v30
	v_mul_f32_e32 v35, 0x3f4c422a, v35
	v_add_f32_e32 v35, v35, v35
	v_mul_f32_e32 v35, 0x3fb8aa3b, v35
	v_exp_f32_e32 v35, v35
	v_mul_f32_e32 v30, 0.5, v30
	v_add_f32_e32 v35, 1.0, v35
	v_rcp_f32_e32 v35, v35
	s_nop 0
	v_fma_f32 v35, v35, -2.0, 1.0
	v_add_f32_e32 v35, 1.0, v35
	v_mul_f32_e32 v30, v30, v35
	v_and_b32_e32 v35, 0xffff0000, v36
	v_fmac_f32_e32 v31, v15, v35
	v_mul_f32_e32 v35, 0x3d372713, v31
	v_mul_f32_e32 v35, v31, v35
	v_fma_f32 v35, v31, v35, v31
	v_mul_f32_e32 v35, 0x3f4c422a, v35
	v_add_f32_e32 v35, v35, v35
	v_mul_f32_e32 v35, 0x3fb8aa3b, v35
	v_exp_f32_e32 v35, v35
	v_mul_f32_e32 v31, 0.5, v31
	v_add_f32_e32 v35, 1.0, v35
	v_rcp_f32_e32 v35, v35
	s_nop 0
	v_fma_f32 v35, v35, -2.0, 1.0
	v_add_f32_e32 v35, 1.0, v35
	v_mul_f32_e32 v31, v31, v35
	v_lshlrev_b32_e32 v35, 16, v37
	v_fmac_f32_e32 v32, v16, v35
	v_mul_f32_e32 v35, 0x3d372713, v32
	v_mul_f32_e32 v35, v32, v35
	v_fma_f32 v35, v32, v35, v32
	v_mul_f32_e32 v35, 0x3f4c422a, v35
	v_add_f32_e32 v35, v35, v35
	v_mul_f32_e32 v35, 0x3fb8aa3b, v35
	v_exp_f32_e32 v35, v35
	v_mul_f32_e32 v32, 0.5, v32
	v_cvt_pk_bf16_f32 v30, v30, v31
	v_add_f32_e32 v35, 1.0, v35
	v_rcp_f32_e32 v35, v35
	s_nop 0
	v_fma_f32 v35, v35, -2.0, 1.0
	v_add_f32_e32 v35, 1.0, v35
	v_mul_f32_e32 v32, v32, v35
	v_and_b32_e32 v35, 0xffff0000, v37
	v_fmac_f32_e32 v33, v17, v35
	v_mul_f32_e32 v35, 0x3d372713, v33
	v_mul_f32_e32 v35, v33, v35
	v_fma_f32 v35, v33, v35, v33
	v_mul_f32_e32 v35, 0x3f4c422a, v35
	v_add_f32_e32 v35, v35, v35
	v_mul_f32_e32 v35, 0x3fb8aa3b, v35
	v_exp_f32_e32 v35, v35
	v_mul_f32_e32 v33, 0.5, v33
	v_add_f32_e32 v35, 1.0, v35
	v_rcp_f32_e32 v35, v35
	s_nop 0
	v_fma_f32 v35, v35, -2.0, 1.0
	v_add_f32_e32 v35, 1.0, v35
	v_mul_f32_e32 v33, v33, v35
	v_cvt_pk_bf16_f32 v31, v32, v33
	v_add_u32_e32 v32, s19, v34
	v_ashrrev_i32_e32 v33, 31, v32
	v_lshlrev_b64 v[32:33], 11, v[32:33]
	v_lshl_add_u64 v[32:33], v[134:135], 0, v[32:33]
	global_store_dwordx2 v[32:33], v[30:31], off
	v_or_b32_e32 v30, 2, v38
	v_ashrrev_i32_e32 v31, 31, v30
	v_lshlrev_b64 v[32:33], 5, v[30:31]
	v_lshl_add_u64 v[32:33], v[136:137], 0, v[32:33]
	s_waitcnt vmcnt(19)
	v_mov_b64_e32 v[32:33], v[176:177]
	v_lshlrev_b32_e32 v31, 16, v32
	v_fmac_f32_e32 v26, v14, v31
	v_mul_f32_e32 v31, 0x3d372713, v26
	v_mul_f32_e32 v31, v26, v31
	v_fma_f32 v31, v26, v31, v26
	v_mul_f32_e32 v31, 0x3f4c422a, v31
	v_add_f32_e32 v31, v31, v31
	v_mul_f32_e32 v31, 0x3fb8aa3b, v31
	v_exp_f32_e32 v31, v31
	v_mul_f32_e32 v26, 0.5, v26
	v_add_f32_e32 v31, 1.0, v31
	v_rcp_f32_e32 v31, v31
	s_nop 0
	v_fma_f32 v31, v31, -2.0, 1.0
	v_add_f32_e32 v31, 1.0, v31
	v_mul_f32_e32 v26, v26, v31
	v_and_b32_e32 v31, 0xffff0000, v32
	v_fmac_f32_e32 v27, v15, v31
	v_mul_f32_e32 v31, 0x3d372713, v27
	v_mul_f32_e32 v31, v27, v31
	v_fma_f32 v31, v27, v31, v27
	v_mul_f32_e32 v31, 0x3f4c422a, v31
	v_add_f32_e32 v31, v31, v31
	v_mul_f32_e32 v31, 0x3fb8aa3b, v31
	v_exp_f32_e32 v31, v31
	v_mul_f32_e32 v27, 0.5, v27
	v_add_f32_e32 v31, 1.0, v31
	v_rcp_f32_e32 v31, v31
	s_nop 0
	v_fma_f32 v31, v31, -2.0, 1.0
	v_add_f32_e32 v31, 1.0, v31
	v_mul_f32_e32 v27, v27, v31
	v_lshlrev_b32_e32 v31, 16, v33
	v_fmac_f32_e32 v28, v16, v31
	v_mul_f32_e32 v31, 0x3d372713, v28
	v_mul_f32_e32 v31, v28, v31
	v_fma_f32 v31, v28, v31, v28
	v_mul_f32_e32 v31, 0x3f4c422a, v31
	v_add_f32_e32 v31, v31, v31
	v_mul_f32_e32 v31, 0x3fb8aa3b, v31
	v_exp_f32_e32 v31, v31
	v_mul_f32_e32 v28, 0.5, v28
	v_cvt_pk_bf16_f32 v26, v26, v27
	v_add_f32_e32 v31, 1.0, v31
	v_rcp_f32_e32 v31, v31
	s_nop 0
	v_fma_f32 v31, v31, -2.0, 1.0
	v_add_f32_e32 v31, 1.0, v31
	v_mul_f32_e32 v28, v28, v31
	v_and_b32_e32 v31, 0xffff0000, v33
	v_fmac_f32_e32 v29, v17, v31
	v_mul_f32_e32 v31, 0x3d372713, v29
	v_mul_f32_e32 v31, v29, v31
	v_fma_f32 v31, v29, v31, v29
	v_mul_f32_e32 v31, 0x3f4c422a, v31
	v_add_f32_e32 v31, v31, v31
	v_mul_f32_e32 v31, 0x3fb8aa3b, v31
	v_exp_f32_e32 v31, v31
	v_mul_f32_e32 v29, 0.5, v29
	v_add_f32_e32 v31, 1.0, v31
	v_rcp_f32_e32 v31, v31
	s_nop 0
	v_fma_f32 v31, v31, -2.0, 1.0
	v_add_f32_e32 v31, 1.0, v31
	v_mul_f32_e32 v29, v29, v31
	v_cvt_pk_bf16_f32 v27, v28, v29
	v_add_u32_e32 v28, s19, v30
	v_ashrrev_i32_e32 v29, 31, v28
	v_lshlrev_b64 v[28:29], 11, v[28:29]
	v_lshl_add_u64 v[28:29], v[134:135], 0, v[28:29]
	global_store_dwordx2 v[28:29], v[26:27], off
	v_or_b32_e32 v26, 3, v38
	v_ashrrev_i32_e32 v27, 31, v26
	v_lshlrev_b64 v[28:29], 5, v[26:27]
	v_lshl_add_u64 v[28:29], v[136:137], 0, v[28:29]
	s_waitcnt vmcnt(18)
	v_mov_b64_e32 v[28:29], v[178:179]
	v_lshlrev_b32_e32 v27, 16, v28
	v_fmac_f32_e32 v22, v14, v27
	v_mul_f32_e32 v27, 0x3d372713, v22
	v_mul_f32_e32 v27, v22, v27
	v_fma_f32 v27, v22, v27, v22
	v_mul_f32_e32 v27, 0x3f4c422a, v27
	v_add_f32_e32 v27, v27, v27
	v_mul_f32_e32 v27, 0x3fb8aa3b, v27
	v_exp_f32_e32 v27, v27
	v_mul_f32_e32 v22, 0.5, v22
	v_add_f32_e32 v27, 1.0, v27
	v_rcp_f32_e32 v27, v27
	s_nop 0
	v_fma_f32 v27, v27, -2.0, 1.0
	v_add_f32_e32 v27, 1.0, v27
	v_mul_f32_e32 v22, v22, v27
	v_and_b32_e32 v27, 0xffff0000, v28
	v_fmac_f32_e32 v23, v15, v27
	v_mul_f32_e32 v27, 0x3d372713, v23
	v_mul_f32_e32 v27, v23, v27
	v_fma_f32 v27, v23, v27, v23
	v_mul_f32_e32 v27, 0x3f4c422a, v27
	v_add_f32_e32 v27, v27, v27
	v_mul_f32_e32 v27, 0x3fb8aa3b, v27
	v_exp_f32_e32 v27, v27
	v_mul_f32_e32 v23, 0.5, v23
	v_add_f32_e32 v27, 1.0, v27
	v_rcp_f32_e32 v27, v27
	s_nop 0
	v_fma_f32 v27, v27, -2.0, 1.0
	v_add_f32_e32 v27, 1.0, v27
	v_mul_f32_e32 v23, v23, v27
	v_lshlrev_b32_e32 v27, 16, v29
	v_fmac_f32_e32 v24, v16, v27
	v_mul_f32_e32 v27, 0x3d372713, v24
	v_mul_f32_e32 v27, v24, v27
	v_fma_f32 v27, v24, v27, v24
	v_mul_f32_e32 v27, 0x3f4c422a, v27
	v_add_f32_e32 v27, v27, v27
	v_mul_f32_e32 v27, 0x3fb8aa3b, v27
	v_exp_f32_e32 v27, v27
	v_mul_f32_e32 v24, 0.5, v24
	v_cvt_pk_bf16_f32 v22, v22, v23
	v_add_f32_e32 v27, 1.0, v27
	v_rcp_f32_e32 v27, v27
	s_nop 0
	v_fma_f32 v27, v27, -2.0, 1.0
	v_add_f32_e32 v27, 1.0, v27
	v_mul_f32_e32 v24, v24, v27
	v_and_b32_e32 v27, 0xffff0000, v29
	v_fmac_f32_e32 v25, v17, v27
	v_mul_f32_e32 v27, 0x3d372713, v25
	v_mul_f32_e32 v27, v25, v27
	v_fma_f32 v27, v25, v27, v25
	v_mul_f32_e32 v27, 0x3f4c422a, v27
	v_add_f32_e32 v27, v27, v27
	v_mul_f32_e32 v27, 0x3fb8aa3b, v27
	v_exp_f32_e32 v27, v27
	v_mul_f32_e32 v25, 0.5, v25
	v_add_f32_e32 v27, 1.0, v27
	v_rcp_f32_e32 v27, v27
	s_nop 0
	v_fma_f32 v27, v27, -2.0, 1.0
	v_add_f32_e32 v27, 1.0, v27
	v_mul_f32_e32 v25, v25, v27
	v_cvt_pk_bf16_f32 v23, v24, v25
	v_add_u32_e32 v24, s19, v26
	v_ashrrev_i32_e32 v25, 31, v24
	v_lshlrev_b64 v[24:25], 11, v[24:25]
	v_lshl_add_u64 v[24:25], v[134:135], 0, v[24:25]
	global_store_dwordx2 v[24:25], v[22:23], off
	v_add_u32_e32 v22, s20, v236
	v_lshl_or_b32 v22, v22, 4, v229
	v_ashrrev_i32_e32 v23, 31, v22
	v_lshlrev_b64 v[24:25], 5, v[22:23]
	v_lshl_add_u64 v[24:25], v[136:137], 0, v[24:25]
	s_waitcnt vmcnt(17)
	v_mov_b64_e32 v[24:25], v[152:153]
	v_lshlrev_b32_e32 v23, 16, v24
	v_fmac_f32_e32 v18, v14, v23
	v_mul_f32_e32 v23, 0x3d372713, v18
	v_mul_f32_e32 v23, v18, v23
	v_fma_f32 v23, v18, v23, v18
	v_mul_f32_e32 v23, 0x3f4c422a, v23
	v_add_f32_e32 v23, v23, v23
	v_mul_f32_e32 v23, 0x3fb8aa3b, v23
	v_exp_f32_e32 v23, v23
	v_mul_f32_e32 v18, 0.5, v18
	v_add_f32_e32 v23, 1.0, v23
	v_rcp_f32_e32 v23, v23
	s_nop 0
	v_fma_f32 v23, v23, -2.0, 1.0
	v_add_f32_e32 v23, 1.0, v23
	v_mul_f32_e32 v18, v18, v23
	v_and_b32_e32 v23, 0xffff0000, v24
	v_fmac_f32_e32 v19, v15, v23
	v_mul_f32_e32 v23, 0x3d372713, v19
	v_mul_f32_e32 v23, v19, v23
	v_fma_f32 v23, v19, v23, v19
	v_mul_f32_e32 v23, 0x3f4c422a, v23
	v_add_f32_e32 v23, v23, v23
	v_mul_f32_e32 v23, 0x3fb8aa3b, v23
	v_exp_f32_e32 v23, v23
	v_mul_f32_e32 v19, 0.5, v19
	v_add_f32_e32 v23, 1.0, v23
	v_rcp_f32_e32 v23, v23
	s_nop 0
	v_fma_f32 v23, v23, -2.0, 1.0
	v_add_f32_e32 v23, 1.0, v23
	v_mul_f32_e32 v19, v19, v23
	v_lshlrev_b32_e32 v23, 16, v25
	v_fmac_f32_e32 v20, v16, v23
	v_mul_f32_e32 v23, 0x3d372713, v20
	v_mul_f32_e32 v23, v20, v23
	v_fma_f32 v23, v20, v23, v20
	v_mul_f32_e32 v23, 0x3f4c422a, v23
	v_add_f32_e32 v23, v23, v23
	v_mul_f32_e32 v23, 0x3fb8aa3b, v23
	v_exp_f32_e32 v23, v23
	v_mul_f32_e32 v20, 0.5, v20
	v_cvt_pk_bf16_f32 v18, v18, v19
	v_add_f32_e32 v23, 1.0, v23
	v_rcp_f32_e32 v23, v23
	s_nop 0
	v_fma_f32 v23, v23, -2.0, 1.0
	v_add_f32_e32 v23, 1.0, v23
	v_mul_f32_e32 v20, v20, v23
	v_and_b32_e32 v23, 0xffff0000, v25
	v_fmac_f32_e32 v21, v17, v23
	v_mul_f32_e32 v23, 0x3d372713, v21
	v_mul_f32_e32 v23, v21, v23
	v_fma_f32 v23, v21, v23, v21
	v_mul_f32_e32 v23, 0x3f4c422a, v23
	v_add_f32_e32 v23, v23, v23
	v_mul_f32_e32 v23, 0x3fb8aa3b, v23
	v_exp_f32_e32 v23, v23
	v_mul_f32_e32 v21, 0.5, v21
	v_add_f32_e32 v23, 1.0, v23
	v_rcp_f32_e32 v23, v23
	s_nop 0
	v_fma_f32 v23, v23, -2.0, 1.0
	v_add_f32_e32 v23, 1.0, v23
	v_mul_f32_e32 v21, v21, v23
	v_cvt_pk_bf16_f32 v19, v20, v21
	v_add_u32_e32 v20, s19, v22
	v_ashrrev_i32_e32 v21, 31, v20
	v_lshlrev_b64 v[20:21], 11, v[20:21]
	v_lshl_add_u64 v[20:21], v[134:135], 0, v[20:21]
	global_store_dwordx2 v[20:21], v[18:19], off
	v_or_b32_e32 v18, 1, v22
	v_ashrrev_i32_e32 v19, 31, v18
	v_lshlrev_b64 v[20:21], 5, v[18:19]
	v_lshl_add_u64 v[20:21], v[136:137], 0, v[20:21]
	s_waitcnt vmcnt(16)
; #define TILE_PMPN(t, pm, pn) do { int gid_ = (t) / nig, fm_ = gid_ * 8, gsz_ = min(nM - fm_, 8); pm = fm_ + (((t) % nig) % gsz_); pn = ((t) % nig) / gsz_; } while (0)
; #define GOFFS(D) do { _Pragma("unroll") for (int i = 0; i < 4; ++i) { int r_, c_; stage_rc2(wid * 1024 + i * 8192 + lane * 16, r_, c_); \
;     offA[i] = (unsigned)(r_ * D.ld1 + c_) * 2u; offB[i] = (unsigned)(r_ * D.K + c_) * 2u; } } while (0)
; template <class DescFn, class EpiFn>
; __device__ __forceinline__ void gemm_phase(int nM, int nN, DescFn dfn, EpiFn efn) {
;     ...
;     t += G;
;     const bool more = t < ntile;
;     if (more) { TILE_PMPN(t, pm, pn); D = dfn(pm, pn); GOFFS(D); GSTAGE(D, 0, 0); }
;     efn(cpm, cpn)(acc, wr, wc, fr, fq);
;     if (!more) break;
;     asm volatile("" : "+s"(D.ld1), "+s"(D.ld2), "+s"(D.K), "+s"(D.nk1));
	v_mov_b64_e32 v[20:21], v[154:155]
	v_lshlrev_b32_e32 v19, 16, v20
	v_fmac_f32_e32 v10, v14, v19
	v_mul_f32_e32 v19, 0x3d372713, v10
	v_mul_f32_e32 v19, v10, v19
	v_fma_f32 v19, v10, v19, v10
	v_mul_f32_e32 v19, 0x3f4c422a, v19
	v_add_f32_e32 v19, v19, v19
	v_mul_f32_e32 v19, 0x3fb8aa3b, v19
	v_exp_f32_e32 v19, v19
	v_mul_f32_e32 v10, 0.5, v10
	v_add_f32_e32 v19, 1.0, v19
	v_rcp_f32_e32 v19, v19
	s_nop 0
	v_fma_f32 v19, v19, -2.0, 1.0
	v_add_f32_e32 v19, 1.0, v19
	v_mul_f32_e32 v10, v10, v19
	v_and_b32_e32 v19, 0xffff0000, v20
	v_fmac_f32_e32 v11, v15, v19
	v_mul_f32_e32 v19, 0x3d372713, v11
	v_mul_f32_e32 v19, v11, v19
	v_fma_f32 v19, v11, v19, v11
	v_mul_f32_e32 v19, 0x3f4c422a, v19
	v_add_f32_e32 v19, v19, v19
	v_mul_f32_e32 v19, 0x3fb8aa3b, v19
	v_exp_f32_e32 v19, v19
	v_mul_f32_e32 v11, 0.5, v11
	v_add_f32_e32 v19, 1.0, v19
	v_rcp_f32_e32 v19, v19
	s_nop 0
	v_fma_f32 v19, v19, -2.0, 1.0
	v_add_f32_e32 v19, 1.0, v19
	v_mul_f32_e32 v11, v11, v19
	v_lshlrev_b32_e32 v19, 16, v21
	v_fmac_f32_e32 v12, v16, v19
	v_mul_f32_e32 v19, 0x3d372713, v12
	v_mul_f32_e32 v19, v12, v19
	v_fma_f32 v19, v12, v19, v12
	v_mul_f32_e32 v19, 0x3f4c422a, v19
	v_add_f32_e32 v19, v19, v19
	v_mul_f32_e32 v19, 0x3fb8aa3b, v19
	v_exp_f32_e32 v19, v19
	v_mul_f32_e32 v12, 0.5, v12
	v_cvt_pk_bf16_f32 v10, v10, v11
	v_add_f32_e32 v19, 1.0, v19
	v_rcp_f32_e32 v19, v19
	s_nop 0
	v_fma_f32 v19, v19, -2.0, 1.0
	v_add_f32_e32 v19, 1.0, v19
	v_mul_f32_e32 v12, v12, v19
	v_and_b32_e32 v19, 0xffff0000, v21
	v_fmac_f32_e32 v13, v17, v19
	v_mul_f32_e32 v19, 0x3d372713, v13
	v_mul_f32_e32 v19, v13, v19
	v_fma_f32 v19, v13, v19, v13
	v_mul_f32_e32 v19, 0x3f4c422a, v19
	v_add_f32_e32 v19, v19, v19
	v_mul_f32_e32 v19, 0x3fb8aa3b, v19
	v_exp_f32_e32 v19, v19
	v_mul_f32_e32 v13, 0.5, v13
	v_add_f32_e32 v19, 1.0, v19
	v_rcp_f32_e32 v19, v19
	s_nop 0
	v_fma_f32 v19, v19, -2.0, 1.0
	v_add_f32_e32 v19, 1.0, v19
	v_mul_f32_e32 v13, v13, v19
	v_cvt_pk_bf16_f32 v11, v12, v13
	v_add_u32_e32 v12, s19, v18
	v_ashrrev_i32_e32 v13, 31, v12
	v_lshlrev_b64 v[12:13], 11, v[12:13]
	v_lshl_add_u64 v[12:13], v[134:135], 0, v[12:13]
	global_store_dwordx2 v[12:13], v[10:11], off
	v_or_b32_e32 v10, 2, v22
	v_ashrrev_i32_e32 v11, 31, v10
	v_lshlrev_b64 v[12:13], 5, v[10:11]
	v_lshl_add_u64 v[12:13], v[136:137], 0, v[12:13]
	s_waitcnt vmcnt(15)
	v_mov_b64_e32 v[12:13], v[156:157]
	v_lshlrev_b32_e32 v11, 16, v12
	v_fmac_f32_e32 v6, v14, v11
	v_mul_f32_e32 v11, 0x3d372713, v6
	v_mul_f32_e32 v11, v6, v11
	v_fma_f32 v11, v6, v11, v6
	v_mul_f32_e32 v11, 0x3f4c422a, v11
	v_add_f32_e32 v11, v11, v11
	v_mul_f32_e32 v11, 0x3fb8aa3b, v11
	v_exp_f32_e32 v11, v11
	v_mul_f32_e32 v6, 0.5, v6
	v_add_f32_e32 v11, 1.0, v11
	v_rcp_f32_e32 v11, v11
	s_nop 0
	v_fma_f32 v11, v11, -2.0, 1.0
	v_add_f32_e32 v11, 1.0, v11
	v_mul_f32_e32 v6, v6, v11
	v_and_b32_e32 v11, 0xffff0000, v12
	v_fmac_f32_e32 v7, v15, v11
	v_mul_f32_e32 v11, 0x3d372713, v7
	v_mul_f32_e32 v11, v7, v11
	v_fma_f32 v11, v7, v11, v7
	v_mul_f32_e32 v11, 0x3f4c422a, v11
	v_add_f32_e32 v11, v11, v11
	v_mul_f32_e32 v11, 0x3fb8aa3b, v11
	v_exp_f32_e32 v11, v11
	v_mul_f32_e32 v7, 0.5, v7
	v_add_f32_e32 v11, 1.0, v11
	v_rcp_f32_e32 v11, v11
	s_nop 0
	v_fma_f32 v11, v11, -2.0, 1.0
	v_add_f32_e32 v11, 1.0, v11
	v_mul_f32_e32 v7, v7, v11
	v_lshlrev_b32_e32 v11, 16, v13
	v_fmac_f32_e32 v8, v16, v11
	v_mul_f32_e32 v11, 0x3d372713, v8
	v_mul_f32_e32 v11, v8, v11
	v_fma_f32 v11, v8, v11, v8
	v_mul_f32_e32 v11, 0x3f4c422a, v11
	v_add_f32_e32 v11, v11, v11
	v_mul_f32_e32 v11, 0x3fb8aa3b, v11
	v_exp_f32_e32 v11, v11
	v_mul_f32_e32 v8, 0.5, v8
	v_cvt_pk_bf16_f32 v6, v6, v7
	v_add_f32_e32 v11, 1.0, v11
	v_rcp_f32_e32 v11, v11
	s_nop 0
	v_fma_f32 v11, v11, -2.0, 1.0
	v_add_f32_e32 v11, 1.0, v11
	v_mul_f32_e32 v8, v8, v11
	v_and_b32_e32 v11, 0xffff0000, v13
	v_fmac_f32_e32 v9, v17, v11
	v_mul_f32_e32 v11, 0x3d372713, v9
	v_mul_f32_e32 v11, v9, v11
	v_fma_f32 v11, v9, v11, v9
	v_mul_f32_e32 v11, 0x3f4c422a, v11
	v_add_f32_e32 v11, v11, v11
	v_mul_f32_e32 v11, 0x3fb8aa3b, v11
	v_exp_f32_e32 v11, v11
	v_mul_f32_e32 v9, 0.5, v9
	v_add_f32_e32 v11, 1.0, v11
	v_rcp_f32_e32 v11, v11
	s_nop 0
	v_fma_f32 v11, v11, -2.0, 1.0
	v_add_f32_e32 v11, 1.0, v11
	v_mul_f32_e32 v9, v9, v11
	v_cvt_pk_bf16_f32 v7, v8, v9
	v_add_u32_e32 v8, s19, v10
	v_ashrrev_i32_e32 v9, 31, v8
	v_lshlrev_b64 v[8:9], 11, v[8:9]
	v_lshl_add_u64 v[8:9], v[134:135], 0, v[8:9]
	global_store_dwordx2 v[8:9], v[6:7], off
	v_or_b32_e32 v6, 3, v22
	v_ashrrev_i32_e32 v7, 31, v6
	v_lshlrev_b64 v[8:9], 5, v[6:7]
	v_lshl_add_u64 v[8:9], v[136:137], 0, v[8:9]
	s_waitcnt vmcnt(14)
	v_mov_b64_e32 v[8:9], v[158:159]
	v_lshlrev_b32_e32 v7, 16, v8
	v_fmac_f32_e32 v2, v14, v7
	v_mul_f32_e32 v7, 0x3d372713, v2
	v_mul_f32_e32 v7, v2, v7
	v_fma_f32 v7, v2, v7, v2
	v_mul_f32_e32 v7, 0x3f4c422a, v7
	v_add_f32_e32 v7, v7, v7
	v_mul_f32_e32 v7, 0x3fb8aa3b, v7
	v_exp_f32_e32 v7, v7
	v_mul_f32_e32 v2, 0.5, v2
	v_add_f32_e32 v7, 1.0, v7
	v_rcp_f32_e32 v7, v7
	s_nop 0
	v_fma_f32 v7, v7, -2.0, 1.0
	v_add_f32_e32 v7, 1.0, v7
	v_mul_f32_e32 v2, v2, v7
	v_and_b32_e32 v7, 0xffff0000, v8
	v_fmac_f32_e32 v3, v15, v7
	v_mul_f32_e32 v7, 0x3d372713, v3
	v_mul_f32_e32 v7, v3, v7
	v_fma_f32 v7, v3, v7, v3
	v_mul_f32_e32 v7, 0x3f4c422a, v7
	v_add_f32_e32 v7, v7, v7
	v_mul_f32_e32 v7, 0x3fb8aa3b, v7
	v_exp_f32_e32 v7, v7
	v_mul_f32_e32 v3, 0.5, v3
	v_add_f32_e32 v7, 1.0, v7
	v_rcp_f32_e32 v7, v7
	s_nop 0
	v_fma_f32 v7, v7, -2.0, 1.0
	v_add_f32_e32 v7, 1.0, v7
	v_mul_f32_e32 v3, v3, v7
	v_lshlrev_b32_e32 v7, 16, v9
	v_fmac_f32_e32 v4, v16, v7
	v_mul_f32_e32 v7, 0x3d372713, v4
	v_mul_f32_e32 v7, v4, v7
	v_fma_f32 v7, v4, v7, v4
	v_mul_f32_e32 v7, 0x3f4c422a, v7
	v_add_f32_e32 v7, v7, v7
	v_mul_f32_e32 v7, 0x3fb8aa3b, v7
	v_exp_f32_e32 v7, v7
	v_mul_f32_e32 v4, 0.5, v4
	v_cvt_pk_bf16_f32 v2, v2, v3
	v_add_f32_e32 v7, 1.0, v7
	v_rcp_f32_e32 v7, v7
	s_nop 0
	v_fma_f32 v7, v7, -2.0, 1.0
	v_add_f32_e32 v7, 1.0, v7
	v_mul_f32_e32 v4, v4, v7
	v_and_b32_e32 v7, 0xffff0000, v9
	v_fmac_f32_e32 v5, v17, v7
	v_mul_f32_e32 v7, 0x3d372713, v5
	v_mul_f32_e32 v7, v5, v7
	v_fma_f32 v7, v5, v7, v5
	v_mul_f32_e32 v7, 0x3f4c422a, v7
	v_add_f32_e32 v7, v7, v7
	v_mul_f32_e32 v7, 0x3fb8aa3b, v7
	v_exp_f32_e32 v7, v7
	v_mul_f32_e32 v5, 0.5, v5
	v_add_f32_e32 v7, 1.0, v7
	v_rcp_f32_e32 v7, v7
	s_nop 0
	v_fma_f32 v7, v7, -2.0, 1.0
	v_add_f32_e32 v7, 1.0, v7
	v_mul_f32_e32 v5, v5, v7
	v_cvt_pk_bf16_f32 v3, v4, v5
	v_add_u32_e32 v4, s19, v6
	v_ashrrev_i32_e32 v5, 31, v4
	v_lshlrev_b64 v[4:5], 11, v[4:5]
	v_lshl_add_u64 v[4:5], v[134:135], 0, v[4:5]
	global_store_dwordx2 v[4:5], v[2:3], off
	s_setprio 0
	s_andn2_b64 vcc, exec, s[16:17]
	s_mov_b64 s[16:17], -1
	s_cbranch_vccnz .LBB0_1412
	s_mov_b64 s[16:17], 0
	s_branch .LBB0_1412
